# merge G-loop address block moved ahead of the second barrier; topk dot loop: the three packed-FMA key chains interleaved with separate temporaries, removing 165 s_nop wait states
# baseline (speedup 1.0000x reference)
; DI int f2key(float f) { int b = __float_as_int(f); return b ^ ((b >> 31) & 0x7fffffff); }
; DI void phase_peer_topk(const Params& P, int layer, char* smem) {
;     ...
;           for (int g = 0; g < 4; ++g) {
;             f32x2 a0 = {0.f, 0.f}, a1 = {0.f, 0.f}, a2 = {0.f, 0.f}, a3 = {0.f, 0.f};
;             const float* k0 = kp + (c * 16 + g * 4) * 64;
; #pragma unroll
;             for (int c4 = 0; c4 < 16; ++c4) {
;               f32x4 b0 = *(const f32x4*)(k0 + c4 * 4), b1 = *(const f32x4*)(k0 + 64 + c4 * 4);
;               f32x4 b2 = *(const f32x4*)(k0 + 128 + c4 * 4), b3 = *(const f32x4*)(k0 + 192 + c4 * 4);
;               a0 += q2[2 * c4] * b0.lo; a0 += q2[2 * c4 + 1] * b0.hi;
;               a1 += q2[2 * c4] * b1.lo; a1 += q2[2 * c4 + 1] * b1.hi;
;               a2 += q2[2 * c4] * b2.lo; a2 += q2[2 * c4 + 1] * b2.hi;
;               a3 += q2[2 * c4] * b3.lo; a3 += q2[2 * c4 + 1] * b3.hi;
;             }
;             const int n = nh * 64 + qh * 32 + c * 16 + g * 4;
;             ck[g * 4 + 0] = (f2key(a0.x + a0.y) & ~127) | (127 - n);
;             ck[g * 4 + 1] = (f2key(a1.x + a1.y) & ~127) | (126 - n);
;             ck[g * 4 + 2] = (f2key(a2.x + a2.y) & ~127) | (125 - n);
;             ck[g * 4 + 3] = (f2key(a3.x + a3.y) & ~127) | (124 - n);
;           }
.LBB0_44:
	v_lshl_add_u32 v145, s4, 12, v124
	ds_read_b128 v[146:149], v145
	ds_read_b128 v[150:153], v145 offset:16
	ds_read_b128 v[154:157], v145 offset:32
	ds_read_b128 v[158:161], v145 offset:48
	ds_read_b128 v[162:165], v145 offset:256
	ds_read_b128 v[174:177], v145 offset:512
	ds_read_b128 v[178:181], v145 offset:768
	s_waitcnt lgkmcnt(6)
	v_pk_fma_f32 v[146:147], v[12:13], v[146:147], 0 op_sel_hi:[1,1,0]
	v_cndmask_b32_e64 v144, 0, 1, s[12:13]
	v_pk_fma_f32 v[166:167], v[14:15], v[148:149], v[146:147]
	s_waitcnt lgkmcnt(2)
	v_pk_fma_f32 v[146:147], v[12:13], v[162:163], 0 op_sel_hi:[1,1,0]
	v_pk_fma_f32 v[150:151], v[8:9], v[150:151], v[166:167]
	v_pk_fma_f32 v[182:183], v[14:15], v[164:165], v[146:147]
	s_waitcnt lgkmcnt(1)
	v_pk_fma_f32 v[146:147], v[12:13], v[174:175], 0 op_sel_hi:[1,1,0]
	v_pk_fma_f32 v[166:167], v[10:11], v[152:153], v[150:151]
	v_pk_fma_f32 v[184:185], v[14:15], v[176:177], v[146:147]
	s_waitcnt lgkmcnt(0)
	v_pk_fma_f32 v[146:147], v[12:13], v[178:179], 0 op_sel_hi:[1,1,0]
	v_pk_fma_f32 v[154:155], v[4:5], v[154:155], v[166:167]
	v_pk_fma_f32 v[178:179], v[14:15], v[180:181], v[146:147]
	ds_read_b128 v[146:149], v145 offset:272
	ds_read_b128 v[162:165], v145 offset:528
	ds_read_b128 v[174:177], v145 offset:784
	v_pk_fma_f32 v[166:167], v[6:7], v[156:157], v[154:155]
	v_cmp_ne_u32_e32 vcc, 1, v144
	s_waitcnt lgkmcnt(2)
	v_pk_fma_f32 v[146:147], v[8:9], v[146:147], v[182:183]
	v_pk_fma_f32 v[158:159], v[0:1], v[158:159], v[166:167]
	v_pk_fma_f32 v[180:181], v[10:11], v[148:149], v[146:147]
	s_waitcnt lgkmcnt(1)
	v_pk_fma_f32 v[146:147], v[8:9], v[162:163], v[184:185]
	v_lshl_or_b32 v144, s4, 4, v143
	v_pk_fma_f32 v[182:183], v[10:11], v[164:165], v[146:147]
	s_waitcnt lgkmcnt(0)
	v_pk_fma_f32 v[146:147], v[8:9], v[174:175], v[178:179]
	s_mov_b64 s[12:13], 0
	v_pk_fma_f32 v[174:175], v[10:11], v[176:177], v[146:147]
	ds_read_b128 v[146:149], v145 offset:288
	ds_read_b128 v[150:153], v145 offset:544
	ds_read_b128 v[162:165], v145 offset:800
	s_and_b64 vcc, exec, vcc
	s_mov_b32 s4, 1
	s_waitcnt lgkmcnt(1)
	v_pk_fma_f32 v[146:147], v[4:5], v[146:147], v[180:181]
	v_pk_fma_f32 v[186:187], v[4:5], v[150:151], v[182:183]
	v_pk_fma_f32 v[176:177], v[6:7], v[148:149], v[146:147]
	s_waitcnt lgkmcnt(0)
	v_pk_fma_f32 v[188:189], v[4:5], v[162:163], v[174:175]
	v_pk_fma_f32 v[178:179], v[6:7], v[152:153], v[186:187]
	v_pk_fma_f32 v[162:163], v[6:7], v[164:165], v[188:189]
	ds_read_b128 v[146:149], v145 offset:304
	ds_read_b128 v[150:153], v145 offset:560
	ds_read_b128 v[154:157], v145 offset:816
	v_pk_fma_f32 v[164:165], v[2:3], v[160:161], v[158:159]
	s_waitcnt lgkmcnt(1)
	v_pk_fma_f32 v[146:147], v[0:1], v[146:147], v[176:177]
	v_pk_fma_f32 v[186:187], v[0:1], v[150:151], v[178:179]
	v_pk_fma_f32 v[166:167], v[2:3], v[148:149], v[146:147]
	s_waitcnt lgkmcnt(0)
	v_pk_fma_f32 v[188:189], v[0:1], v[154:155], v[162:163]
	v_pk_fma_f32 v[174:175], v[2:3], v[152:153], v[186:187]
	v_pk_fma_f32 v[162:163], v[2:3], v[156:157], v[188:189]
	ds_read_b128 v[146:149], v145 offset:64
	ds_read_b128 v[150:153], v145 offset:320
	ds_read_b128 v[154:157], v145 offset:576
	ds_read_b128 v[158:161], v145 offset:832
	s_waitcnt lgkmcnt(3)
	v_pk_fma_f32 v[146:147], v[28:29], v[146:147], v[164:165]
	s_nop 0
	v_pk_fma_f32 v[164:165], v[30:31], v[148:149], v[146:147]
	s_waitcnt lgkmcnt(1)
	v_pk_fma_f32 v[146:147], v[28:29], v[150:151], v[166:167]
	v_pk_fma_f32 v[186:187], v[28:29], v[154:155], v[174:175]
	v_pk_fma_f32 v[166:167], v[30:31], v[152:153], v[146:147]
	s_waitcnt lgkmcnt(0)
	v_pk_fma_f32 v[188:189], v[28:29], v[158:159], v[162:163]
	v_pk_fma_f32 v[174:175], v[30:31], v[156:157], v[186:187]
	v_pk_fma_f32 v[162:163], v[30:31], v[160:161], v[188:189]
	ds_read_b128 v[146:149], v145 offset:80
	ds_read_b128 v[150:153], v145 offset:336
	ds_read_b128 v[154:157], v145 offset:592
	ds_read_b128 v[158:161], v145 offset:848
	s_waitcnt lgkmcnt(3)
	v_pk_fma_f32 v[146:147], v[24:25], v[146:147], v[164:165]
	s_nop 0
	v_pk_fma_f32 v[164:165], v[26:27], v[148:149], v[146:147]
	s_waitcnt lgkmcnt(1)
	v_pk_fma_f32 v[146:147], v[24:25], v[150:151], v[166:167]
	v_pk_fma_f32 v[186:187], v[24:25], v[154:155], v[174:175]
	v_pk_fma_f32 v[166:167], v[26:27], v[152:153], v[146:147]
	s_waitcnt lgkmcnt(0)
	v_pk_fma_f32 v[188:189], v[24:25], v[158:159], v[162:163]
	v_pk_fma_f32 v[174:175], v[26:27], v[156:157], v[186:187]
	v_pk_fma_f32 v[162:163], v[26:27], v[160:161], v[188:189]
	ds_read_b128 v[146:149], v145 offset:96
	ds_read_b128 v[150:153], v145 offset:352
	ds_read_b128 v[154:157], v145 offset:608
	ds_read_b128 v[158:161], v145 offset:864
	s_waitcnt lgkmcnt(3)
	v_pk_fma_f32 v[146:147], v[20:21], v[146:147], v[164:165]
	s_nop 0
	v_pk_fma_f32 v[164:165], v[22:23], v[148:149], v[146:147]
	s_waitcnt lgkmcnt(1)
	v_pk_fma_f32 v[146:147], v[20:21], v[150:151], v[166:167]
	v_pk_fma_f32 v[186:187], v[20:21], v[154:155], v[174:175]
	v_pk_fma_f32 v[166:167], v[22:23], v[152:153], v[146:147]
	s_waitcnt lgkmcnt(0)
	v_pk_fma_f32 v[188:189], v[20:21], v[158:159], v[162:163]
	v_pk_fma_f32 v[174:175], v[22:23], v[156:157], v[186:187]
	v_pk_fma_f32 v[162:163], v[22:23], v[160:161], v[188:189]
	ds_read_b128 v[146:149], v145 offset:112
	ds_read_b128 v[150:153], v145 offset:368
	ds_read_b128 v[154:157], v145 offset:624
	ds_read_b128 v[158:161], v145 offset:880
	s_waitcnt lgkmcnt(3)
	v_pk_fma_f32 v[146:147], v[16:17], v[146:147], v[164:165]
	s_nop 0
	v_pk_fma_f32 v[164:165], v[18:19], v[148:149], v[146:147]
	s_waitcnt lgkmcnt(1)
	v_pk_fma_f32 v[146:147], v[16:17], v[150:151], v[166:167]
	v_pk_fma_f32 v[186:187], v[16:17], v[154:155], v[174:175]
	v_pk_fma_f32 v[166:167], v[18:19], v[152:153], v[146:147]
	s_waitcnt lgkmcnt(0)
; DI int f2key(float f) { int b = __float_as_int(f); return b ^ ((b >> 31) & 0x7fffffff); }
; DI void phase_peer_topk(const Params& P, int layer, char* smem) {
;     ...
;           for (int g = 0; g < 4; ++g) {
;             f32x2 a0 = {0.f, 0.f}, a1 = {0.f, 0.f}, a2 = {0.f, 0.f}, a3 = {0.f, 0.f};
;             const float* k0 = kp + (c * 16 + g * 4) * 64;
; #pragma unroll
;             for (int c4 = 0; c4 < 16; ++c4) {
;               f32x4 b0 = *(const f32x4*)(k0 + c4 * 4), b1 = *(const f32x4*)(k0 + 64 + c4 * 4);
;               f32x4 b2 = *(const f32x4*)(k0 + 128 + c4 * 4), b3 = *(const f32x4*)(k0 + 192 + c4 * 4);
;               a0 += q2[2 * c4] * b0.lo; a0 += q2[2 * c4 + 1] * b0.hi;
;               a1 += q2[2 * c4] * b1.lo; a1 += q2[2 * c4 + 1] * b1.hi;
;               a2 += q2[2 * c4] * b2.lo; a2 += q2[2 * c4 + 1] * b2.hi;
;               a3 += q2[2 * c4] * b3.lo; a3 += q2[2 * c4 + 1] * b3.hi;
;             }
;             const int n = nh * 64 + qh * 32 + c * 16 + g * 4;
;             ck[g * 4 + 0] = (f2key(a0.x + a0.y) & ~127) | (127 - n);
;             ck[g * 4 + 1] = (f2key(a1.x + a1.y) & ~127) | (126 - n);
;             ck[g * 4 + 2] = (f2key(a2.x + a2.y) & ~127) | (125 - n);
;             ck[g * 4 + 3] = (f2key(a3.x + a3.y) & ~127) | (124 - n);
;           }
	v_pk_fma_f32 v[188:189], v[16:17], v[158:159], v[162:163]
	v_pk_fma_f32 v[174:175], v[18:19], v[156:157], v[186:187]
	v_pk_fma_f32 v[162:163], v[18:19], v[160:161], v[188:189]
	ds_read_b128 v[146:149], v145 offset:128
	ds_read_b128 v[150:153], v145 offset:384
	ds_read_b128 v[154:157], v145 offset:640
	ds_read_b128 v[158:161], v145 offset:896
	s_waitcnt lgkmcnt(3)
	v_pk_fma_f32 v[146:147], v[44:45], v[146:147], v[164:165]
	s_nop 0
	v_pk_fma_f32 v[164:165], v[46:47], v[148:149], v[146:147]
	s_waitcnt lgkmcnt(1)
	v_pk_fma_f32 v[146:147], v[44:45], v[150:151], v[166:167]
	v_pk_fma_f32 v[186:187], v[44:45], v[154:155], v[174:175]
	v_pk_fma_f32 v[166:167], v[46:47], v[152:153], v[146:147]
	s_waitcnt lgkmcnt(0)
	v_pk_fma_f32 v[188:189], v[44:45], v[158:159], v[162:163]
	v_pk_fma_f32 v[174:175], v[46:47], v[156:157], v[186:187]
	v_pk_fma_f32 v[162:163], v[46:47], v[160:161], v[188:189]
	ds_read_b128 v[146:149], v145 offset:144
	ds_read_b128 v[150:153], v145 offset:400
	ds_read_b128 v[154:157], v145 offset:656
	ds_read_b128 v[158:161], v145 offset:912
	s_waitcnt lgkmcnt(3)
	v_pk_fma_f32 v[146:147], v[40:41], v[146:147], v[164:165]
	s_nop 0
	v_pk_fma_f32 v[164:165], v[42:43], v[148:149], v[146:147]
	s_waitcnt lgkmcnt(1)
	v_pk_fma_f32 v[146:147], v[40:41], v[150:151], v[166:167]
	v_pk_fma_f32 v[186:187], v[40:41], v[154:155], v[174:175]
	v_pk_fma_f32 v[166:167], v[42:43], v[152:153], v[146:147]
	s_waitcnt lgkmcnt(0)
	v_pk_fma_f32 v[188:189], v[40:41], v[158:159], v[162:163]
	v_pk_fma_f32 v[174:175], v[42:43], v[156:157], v[186:187]
	v_pk_fma_f32 v[162:163], v[42:43], v[160:161], v[188:189]
	ds_read_b128 v[146:149], v145 offset:160
	ds_read_b128 v[150:153], v145 offset:416
	ds_read_b128 v[154:157], v145 offset:672
	ds_read_b128 v[158:161], v145 offset:928
	s_waitcnt lgkmcnt(3)
	v_pk_fma_f32 v[146:147], v[36:37], v[146:147], v[164:165]
	s_nop 0
	v_pk_fma_f32 v[164:165], v[38:39], v[148:149], v[146:147]
	s_waitcnt lgkmcnt(1)
	v_pk_fma_f32 v[146:147], v[36:37], v[150:151], v[166:167]
	v_pk_fma_f32 v[186:187], v[36:37], v[154:155], v[174:175]
	v_pk_fma_f32 v[166:167], v[38:39], v[152:153], v[146:147]
	s_waitcnt lgkmcnt(0)
	v_pk_fma_f32 v[188:189], v[36:37], v[158:159], v[162:163]
	v_pk_fma_f32 v[174:175], v[38:39], v[156:157], v[186:187]
	v_pk_fma_f32 v[162:163], v[38:39], v[160:161], v[188:189]
	ds_read_b128 v[146:149], v145 offset:176
	ds_read_b128 v[150:153], v145 offset:432
	ds_read_b128 v[154:157], v145 offset:688
	ds_read_b128 v[158:161], v145 offset:944
	s_waitcnt lgkmcnt(3)
	v_pk_fma_f32 v[146:147], v[32:33], v[146:147], v[164:165]
	s_nop 0
	v_pk_fma_f32 v[164:165], v[34:35], v[148:149], v[146:147]
	s_waitcnt lgkmcnt(1)
	v_pk_fma_f32 v[146:147], v[32:33], v[150:151], v[166:167]
	v_pk_fma_f32 v[186:187], v[32:33], v[154:155], v[174:175]
	v_pk_fma_f32 v[166:167], v[34:35], v[152:153], v[146:147]
	s_waitcnt lgkmcnt(0)
	v_pk_fma_f32 v[188:189], v[32:33], v[158:159], v[162:163]
	v_pk_fma_f32 v[174:175], v[34:35], v[156:157], v[186:187]
	v_pk_fma_f32 v[162:163], v[34:35], v[160:161], v[188:189]
	ds_read_b128 v[146:149], v145 offset:192
	ds_read_b128 v[150:153], v145 offset:448
	ds_read_b128 v[154:157], v145 offset:704
	ds_read_b128 v[158:161], v145 offset:960
	s_waitcnt lgkmcnt(3)
	v_pk_fma_f32 v[146:147], v[60:61], v[146:147], v[164:165]
	s_nop 0
	v_pk_fma_f32 v[164:165], v[62:63], v[148:149], v[146:147]
	s_waitcnt lgkmcnt(1)
	v_pk_fma_f32 v[146:147], v[60:61], v[150:151], v[166:167]
	v_pk_fma_f32 v[186:187], v[60:61], v[154:155], v[174:175]
	v_pk_fma_f32 v[166:167], v[62:63], v[152:153], v[146:147]
	s_waitcnt lgkmcnt(0)
	v_pk_fma_f32 v[188:189], v[60:61], v[158:159], v[162:163]
	v_pk_fma_f32 v[174:175], v[62:63], v[156:157], v[186:187]
	v_pk_fma_f32 v[162:163], v[62:63], v[160:161], v[188:189]
	ds_read_b128 v[146:149], v145 offset:208
	ds_read_b128 v[150:153], v145 offset:464
	ds_read_b128 v[154:157], v145 offset:720
	ds_read_b128 v[158:161], v145 offset:976
	s_waitcnt lgkmcnt(3)
	v_pk_fma_f32 v[146:147], v[56:57], v[146:147], v[164:165]
	s_nop 0
	v_pk_fma_f32 v[164:165], v[58:59], v[148:149], v[146:147]
	s_waitcnt lgkmcnt(1)
	v_pk_fma_f32 v[146:147], v[56:57], v[150:151], v[166:167]
	v_pk_fma_f32 v[186:187], v[56:57], v[154:155], v[174:175]
	v_pk_fma_f32 v[166:167], v[58:59], v[152:153], v[146:147]
	s_waitcnt lgkmcnt(0)
	v_pk_fma_f32 v[188:189], v[56:57], v[158:159], v[162:163]
	v_pk_fma_f32 v[174:175], v[58:59], v[156:157], v[186:187]
	v_pk_fma_f32 v[162:163], v[58:59], v[160:161], v[188:189]
	ds_read_b128 v[146:149], v145 offset:224
	ds_read_b128 v[150:153], v145 offset:480
	ds_read_b128 v[154:157], v145 offset:736
	ds_read_b128 v[158:161], v145 offset:992
	s_waitcnt lgkmcnt(3)
	v_pk_fma_f32 v[146:147], v[52:53], v[146:147], v[164:165]
	s_nop 0
	v_pk_fma_f32 v[164:165], v[54:55], v[148:149], v[146:147]
	s_waitcnt lgkmcnt(1)
	v_pk_fma_f32 v[146:147], v[52:53], v[150:151], v[166:167]
	v_pk_fma_f32 v[186:187], v[52:53], v[154:155], v[174:175]
	v_pk_fma_f32 v[166:167], v[54:55], v[152:153], v[146:147]
	s_waitcnt lgkmcnt(0)
	v_pk_fma_f32 v[188:189], v[52:53], v[158:159], v[162:163]
	v_pk_fma_f32 v[174:175], v[54:55], v[156:157], v[186:187]
	v_pk_fma_f32 v[162:163], v[54:55], v[160:161], v[188:189]
	ds_read_b128 v[146:149], v145 offset:240
	ds_read_b128 v[150:153], v145 offset:496
	ds_read_b128 v[154:157], v145 offset:752
	ds_read_b128 v[158:161], v145 offset:1008
	s_waitcnt lgkmcnt(3)
	v_pk_fma_f32 v[146:147], v[48:49], v[146:147], v[164:165]
	s_nop 0
	v_pk_fma_f32 v[146:147], v[50:51], v[148:149], v[146:147]
	s_waitcnt lgkmcnt(2)
	v_pk_fma_f32 v[148:149], v[48:49], v[150:151], v[166:167]
	s_waitcnt lgkmcnt(1)
; DI int f2key(float f) { int b = __float_as_int(f); return b ^ ((b >> 31) & 0x7fffffff); }
; DI void phase_peer_topk(const Params& P, int layer, char* smem) {
;     ...
;           for (int g = 0; g < 4; ++g) {
;             f32x2 a0 = {0.f, 0.f}, a1 = {0.f, 0.f}, a2 = {0.f, 0.f}, a3 = {0.f, 0.f};
;             const float* k0 = kp + (c * 16 + g * 4) * 64;
; #pragma unroll
;             for (int c4 = 0; c4 < 16; ++c4) {
;               f32x4 b0 = *(const f32x4*)(k0 + c4 * 4), b1 = *(const f32x4*)(k0 + 64 + c4 * 4);
;               f32x4 b2 = *(const f32x4*)(k0 + 128 + c4 * 4), b3 = *(const f32x4*)(k0 + 192 + c4 * 4);
;               a0 += q2[2 * c4] * b0.lo; a0 += q2[2 * c4 + 1] * b0.hi;
;               a1 += q2[2 * c4] * b1.lo; a1 += q2[2 * c4 + 1] * b1.hi;
;               a2 += q2[2 * c4] * b2.lo; a2 += q2[2 * c4 + 1] * b2.hi;
;               a3 += q2[2 * c4] * b3.lo; a3 += q2[2 * c4 + 1] * b3.hi;
;             }
;             const int n = nh * 64 + qh * 32 + c * 16 + g * 4;
;             ck[g * 4 + 0] = (f2key(a0.x + a0.y) & ~127) | (127 - n);
;             ck[g * 4 + 1] = (f2key(a1.x + a1.y) & ~127) | (126 - n);
;             ck[g * 4 + 2] = (f2key(a2.x + a2.y) & ~127) | (125 - n);
;             ck[g * 4 + 3] = (f2key(a3.x + a3.y) & ~127) | (124 - n);
;           }
	v_pk_fma_f32 v[150:151], v[48:49], v[154:155], v[174:175]
	v_pk_fma_f32 v[148:149], v[50:51], v[152:153], v[148:149]
	v_mov_b32_e32 v155, v146
	v_mov_b32_e32 v154, v148
	v_mov_b32_e32 v146, v149
	v_pk_add_f32 v[148:149], v[154:155], v[146:147]
	v_pk_fma_f32 v[150:151], v[50:51], v[156:157], v[150:151]
	v_ashrrev_i32_e32 v146, 31, v149
	v_sub_u32_e32 v156, 0x7f, v144
	v_and_b32_e32 v146, 0x7fffff80, v146
	v_and_b32_e32 v147, 0xffffff80, v149
	s_waitcnt lgkmcnt(0)
	v_pk_fma_f32 v[152:153], v[48:49], v[158:159], v[162:163]
	v_bitop3_b32 v146, v146, v156, v147 bitop3:0xde
	v_ashrrev_i32_e32 v147, 31, v148
	v_pk_fma_f32 v[152:153], v[50:51], v[160:161], v[152:153]
	v_and_b32_e32 v147, 0x7fffff80, v147
	v_and_b32_e32 v148, 0xffffff80, v148
	v_sub_u32_e32 v149, 0x7e, v144
	v_bitop3_b32 v147, v147, v149, v148 bitop3:0xde
	v_mov_b32_e32 v148, v152
	v_mov_b32_e32 v149, v150
	v_mov_b32_e32 v150, v153
	v_pk_add_f32 v[150:151], v[148:149], v[150:151]
	v_sub_u32_e32 v154, 0x7d, v144
	v_ashrrev_i32_e32 v148, 31, v151
	v_and_b32_e32 v148, 0x7fffff80, v148
	v_and_b32_e32 v149, 0xffffff80, v151
	v_bitop3_b32 v148, v148, v154, v149 bitop3:0xde
	v_ashrrev_i32_e32 v149, 31, v150
	v_and_b32_e32 v149, 0x7fffff80, v149
	v_and_b32_e32 v150, 0xffffff80, v150
	v_sub_u32_e32 v151, 0x7c, v144
	v_bitop3_b32 v149, v149, v151, v150 bitop3:0xde
	ds_read_b128 v[150:153], v145 offset:1024
	ds_read_b128 v[154:157], v145 offset:1280
	ds_read_b128 v[158:161], v145 offset:1536
	ds_read_b128 v[162:165], v145 offset:1792
	s_waitcnt lgkmcnt(3)
	v_pk_fma_f32 v[150:151], v[12:13], v[150:151], 0 op_sel_hi:[1,1,0]
	s_nop 0
	v_pk_fma_f32 v[166:167], v[14:15], v[152:153], v[150:151]
	s_waitcnt lgkmcnt(2)
	v_pk_fma_f32 v[150:151], v[12:13], v[154:155], 0 op_sel_hi:[1,1,0]
	s_nop 0
	v_pk_fma_f32 v[174:175], v[14:15], v[156:157], v[150:151]
	s_waitcnt lgkmcnt(1)
	v_pk_fma_f32 v[150:151], v[12:13], v[158:159], 0 op_sel_hi:[1,1,0]
	s_nop 0
	v_pk_fma_f32 v[176:177], v[14:15], v[160:161], v[150:151]
	s_waitcnt lgkmcnt(0)
	v_pk_fma_f32 v[150:151], v[12:13], v[162:163], 0 op_sel_hi:[1,1,0]
	s_nop 0
	v_pk_fma_f32 v[178:179], v[14:15], v[164:165], v[150:151]
	ds_read_b128 v[150:153], v145 offset:1040
	ds_read_b128 v[154:157], v145 offset:1296
	ds_read_b128 v[158:161], v145 offset:1552
	ds_read_b128 v[162:165], v145 offset:1808
	s_waitcnt lgkmcnt(3)
	v_pk_fma_f32 v[150:151], v[8:9], v[150:151], v[166:167]
	s_nop 0
	v_pk_fma_f32 v[166:167], v[10:11], v[152:153], v[150:151]
	s_waitcnt lgkmcnt(1)
	v_pk_fma_f32 v[150:151], v[8:9], v[154:155], v[174:175]
	v_pk_fma_f32 v[186:187], v[8:9], v[158:159], v[176:177]
	v_pk_fma_f32 v[174:175], v[10:11], v[156:157], v[150:151]
	s_waitcnt lgkmcnt(0)
	v_pk_fma_f32 v[188:189], v[8:9], v[162:163], v[178:179]
	v_pk_fma_f32 v[176:177], v[10:11], v[160:161], v[186:187]
	v_pk_fma_f32 v[178:179], v[10:11], v[164:165], v[188:189]
	ds_read_b128 v[150:153], v145 offset:1056
	ds_read_b128 v[154:157], v145 offset:1312
	ds_read_b128 v[158:161], v145 offset:1568
	ds_read_b128 v[162:165], v145 offset:1824
	s_waitcnt lgkmcnt(3)
	v_pk_fma_f32 v[150:151], v[4:5], v[150:151], v[166:167]
	s_nop 0
	v_pk_fma_f32 v[166:167], v[6:7], v[152:153], v[150:151]
	s_waitcnt lgkmcnt(1)
	v_pk_fma_f32 v[150:151], v[4:5], v[154:155], v[174:175]
	v_pk_fma_f32 v[186:187], v[4:5], v[158:159], v[176:177]
	v_pk_fma_f32 v[174:175], v[6:7], v[156:157], v[150:151]
	s_waitcnt lgkmcnt(0)
	v_pk_fma_f32 v[188:189], v[4:5], v[162:163], v[178:179]
	v_pk_fma_f32 v[176:177], v[6:7], v[160:161], v[186:187]
	v_pk_fma_f32 v[178:179], v[6:7], v[164:165], v[188:189]
	ds_read_b128 v[150:153], v145 offset:1072
	ds_read_b128 v[154:157], v145 offset:1328
	ds_read_b128 v[158:161], v145 offset:1584
	ds_read_b128 v[162:165], v145 offset:1840
	s_waitcnt lgkmcnt(3)
	v_pk_fma_f32 v[150:151], v[0:1], v[150:151], v[166:167]
	s_nop 0
	v_pk_fma_f32 v[166:167], v[2:3], v[152:153], v[150:151]
	s_waitcnt lgkmcnt(1)
	v_pk_fma_f32 v[150:151], v[0:1], v[154:155], v[174:175]
	v_pk_fma_f32 v[186:187], v[0:1], v[158:159], v[176:177]
	v_pk_fma_f32 v[174:175], v[2:3], v[156:157], v[150:151]
	s_waitcnt lgkmcnt(0)
	v_pk_fma_f32 v[188:189], v[0:1], v[162:163], v[178:179]
	v_pk_fma_f32 v[176:177], v[2:3], v[160:161], v[186:187]
	v_pk_fma_f32 v[178:179], v[2:3], v[164:165], v[188:189]
	ds_read_b128 v[150:153], v145 offset:1088
	ds_read_b128 v[154:157], v145 offset:1344
	ds_read_b128 v[158:161], v145 offset:1600
	ds_read_b128 v[162:165], v145 offset:1856
	s_waitcnt lgkmcnt(3)
	v_pk_fma_f32 v[150:151], v[28:29], v[150:151], v[166:167]
	s_nop 0
	v_pk_fma_f32 v[166:167], v[30:31], v[152:153], v[150:151]
	s_waitcnt lgkmcnt(1)
	v_pk_fma_f32 v[150:151], v[28:29], v[154:155], v[174:175]
	v_pk_fma_f32 v[186:187], v[28:29], v[158:159], v[176:177]
	v_pk_fma_f32 v[174:175], v[30:31], v[156:157], v[150:151]
	s_waitcnt lgkmcnt(0)
	v_pk_fma_f32 v[188:189], v[28:29], v[162:163], v[178:179]
	v_pk_fma_f32 v[176:177], v[30:31], v[160:161], v[186:187]
	v_pk_fma_f32 v[178:179], v[30:31], v[164:165], v[188:189]
	ds_read_b128 v[150:153], v145 offset:1104
	ds_read_b128 v[154:157], v145 offset:1360
	ds_read_b128 v[158:161], v145 offset:1616
	ds_read_b128 v[162:165], v145 offset:1872
	s_waitcnt lgkmcnt(3)
	v_pk_fma_f32 v[150:151], v[24:25], v[150:151], v[166:167]
	s_nop 0
	v_pk_fma_f32 v[166:167], v[26:27], v[152:153], v[150:151]
	s_waitcnt lgkmcnt(1)
	v_pk_fma_f32 v[150:151], v[24:25], v[154:155], v[174:175]
	v_pk_fma_f32 v[186:187], v[24:25], v[158:159], v[176:177]
	v_pk_fma_f32 v[174:175], v[26:27], v[156:157], v[150:151]
	s_waitcnt lgkmcnt(0)
; DI int f2key(float f) { int b = __float_as_int(f); return b ^ ((b >> 31) & 0x7fffffff); }
; DI void phase_peer_topk(const Params& P, int layer, char* smem) {
;     ...
;           for (int g = 0; g < 4; ++g) {
;             f32x2 a0 = {0.f, 0.f}, a1 = {0.f, 0.f}, a2 = {0.f, 0.f}, a3 = {0.f, 0.f};
;             const float* k0 = kp + (c * 16 + g * 4) * 64;
; #pragma unroll
;             for (int c4 = 0; c4 < 16; ++c4) {
;               f32x4 b0 = *(const f32x4*)(k0 + c4 * 4), b1 = *(const f32x4*)(k0 + 64 + c4 * 4);
;               f32x4 b2 = *(const f32x4*)(k0 + 128 + c4 * 4), b3 = *(const f32x4*)(k0 + 192 + c4 * 4);
;               a0 += q2[2 * c4] * b0.lo; a0 += q2[2 * c4 + 1] * b0.hi;
;               a1 += q2[2 * c4] * b1.lo; a1 += q2[2 * c4 + 1] * b1.hi;
;               a2 += q2[2 * c4] * b2.lo; a2 += q2[2 * c4 + 1] * b2.hi;
;               a3 += q2[2 * c4] * b3.lo; a3 += q2[2 * c4 + 1] * b3.hi;
;             }
;             const int n = nh * 64 + qh * 32 + c * 16 + g * 4;
;             ck[g * 4 + 0] = (f2key(a0.x + a0.y) & ~127) | (127 - n);
;             ck[g * 4 + 1] = (f2key(a1.x + a1.y) & ~127) | (126 - n);
;             ck[g * 4 + 2] = (f2key(a2.x + a2.y) & ~127) | (125 - n);
;             ck[g * 4 + 3] = (f2key(a3.x + a3.y) & ~127) | (124 - n);
;           }
	v_pk_fma_f32 v[188:189], v[24:25], v[162:163], v[178:179]
	v_pk_fma_f32 v[176:177], v[26:27], v[160:161], v[186:187]
	v_pk_fma_f32 v[178:179], v[26:27], v[164:165], v[188:189]
	ds_read_b128 v[150:153], v145 offset:1120
	ds_read_b128 v[154:157], v145 offset:1376
	ds_read_b128 v[158:161], v145 offset:1632
	ds_read_b128 v[162:165], v145 offset:1888
	s_waitcnt lgkmcnt(3)
	v_pk_fma_f32 v[150:151], v[20:21], v[150:151], v[166:167]
	s_nop 0
	v_pk_fma_f32 v[166:167], v[22:23], v[152:153], v[150:151]
	s_waitcnt lgkmcnt(1)
	v_pk_fma_f32 v[150:151], v[20:21], v[154:155], v[174:175]
	v_pk_fma_f32 v[186:187], v[20:21], v[158:159], v[176:177]
	v_pk_fma_f32 v[174:175], v[22:23], v[156:157], v[150:151]
	s_waitcnt lgkmcnt(0)
	v_pk_fma_f32 v[188:189], v[20:21], v[162:163], v[178:179]
	v_pk_fma_f32 v[176:177], v[22:23], v[160:161], v[186:187]
	v_pk_fma_f32 v[178:179], v[22:23], v[164:165], v[188:189]
	ds_read_b128 v[150:153], v145 offset:1136
	ds_read_b128 v[154:157], v145 offset:1392
	ds_read_b128 v[158:161], v145 offset:1648
	ds_read_b128 v[162:165], v145 offset:1904
	s_waitcnt lgkmcnt(3)
	v_pk_fma_f32 v[150:151], v[16:17], v[150:151], v[166:167]
	s_nop 0
	v_pk_fma_f32 v[166:167], v[18:19], v[152:153], v[150:151]
	s_waitcnt lgkmcnt(1)
	v_pk_fma_f32 v[150:151], v[16:17], v[154:155], v[174:175]
	v_pk_fma_f32 v[186:187], v[16:17], v[158:159], v[176:177]
	v_pk_fma_f32 v[174:175], v[18:19], v[156:157], v[150:151]
	s_waitcnt lgkmcnt(0)
	v_pk_fma_f32 v[188:189], v[16:17], v[162:163], v[178:179]
	v_pk_fma_f32 v[176:177], v[18:19], v[160:161], v[186:187]
	v_pk_fma_f32 v[178:179], v[18:19], v[164:165], v[188:189]
	ds_read_b128 v[150:153], v145 offset:1152
	ds_read_b128 v[154:157], v145 offset:1408
	ds_read_b128 v[158:161], v145 offset:1664
	ds_read_b128 v[162:165], v145 offset:1920
	s_waitcnt lgkmcnt(3)
	v_pk_fma_f32 v[150:151], v[44:45], v[150:151], v[166:167]
	s_nop 0
	v_pk_fma_f32 v[166:167], v[46:47], v[152:153], v[150:151]
	s_waitcnt lgkmcnt(1)
	v_pk_fma_f32 v[150:151], v[44:45], v[154:155], v[174:175]
	v_pk_fma_f32 v[186:187], v[44:45], v[158:159], v[176:177]
	v_pk_fma_f32 v[174:175], v[46:47], v[156:157], v[150:151]
	s_waitcnt lgkmcnt(0)
	v_pk_fma_f32 v[188:189], v[44:45], v[162:163], v[178:179]
	v_pk_fma_f32 v[176:177], v[46:47], v[160:161], v[186:187]
	v_pk_fma_f32 v[178:179], v[46:47], v[164:165], v[188:189]
	ds_read_b128 v[150:153], v145 offset:1168
	ds_read_b128 v[154:157], v145 offset:1424
	ds_read_b128 v[158:161], v145 offset:1680
	ds_read_b128 v[162:165], v145 offset:1936
	s_waitcnt lgkmcnt(3)
	v_pk_fma_f32 v[150:151], v[40:41], v[150:151], v[166:167]
	s_nop 0
	v_pk_fma_f32 v[166:167], v[42:43], v[152:153], v[150:151]
	s_waitcnt lgkmcnt(1)
	v_pk_fma_f32 v[150:151], v[40:41], v[154:155], v[174:175]
	v_pk_fma_f32 v[186:187], v[40:41], v[158:159], v[176:177]
	v_pk_fma_f32 v[174:175], v[42:43], v[156:157], v[150:151]
	s_waitcnt lgkmcnt(0)
	v_pk_fma_f32 v[188:189], v[40:41], v[162:163], v[178:179]
	v_pk_fma_f32 v[176:177], v[42:43], v[160:161], v[186:187]
	v_pk_fma_f32 v[178:179], v[42:43], v[164:165], v[188:189]
	ds_read_b128 v[150:153], v145 offset:1184
	ds_read_b128 v[154:157], v145 offset:1440
	ds_read_b128 v[158:161], v145 offset:1696
	ds_read_b128 v[162:165], v145 offset:1952
	s_waitcnt lgkmcnt(3)
	v_pk_fma_f32 v[150:151], v[36:37], v[150:151], v[166:167]
	s_nop 0
	v_pk_fma_f32 v[166:167], v[38:39], v[152:153], v[150:151]
	s_waitcnt lgkmcnt(1)
	v_pk_fma_f32 v[150:151], v[36:37], v[154:155], v[174:175]
	v_pk_fma_f32 v[186:187], v[36:37], v[158:159], v[176:177]
	v_pk_fma_f32 v[174:175], v[38:39], v[156:157], v[150:151]
	s_waitcnt lgkmcnt(0)
	v_pk_fma_f32 v[188:189], v[36:37], v[162:163], v[178:179]
	v_pk_fma_f32 v[176:177], v[38:39], v[160:161], v[186:187]
	v_pk_fma_f32 v[178:179], v[38:39], v[164:165], v[188:189]
	ds_read_b128 v[150:153], v145 offset:1200
	ds_read_b128 v[154:157], v145 offset:1456
	ds_read_b128 v[158:161], v145 offset:1712
	ds_read_b128 v[162:165], v145 offset:1968
	s_waitcnt lgkmcnt(3)
	v_pk_fma_f32 v[150:151], v[32:33], v[150:151], v[166:167]
	s_nop 0
	v_pk_fma_f32 v[166:167], v[34:35], v[152:153], v[150:151]
	s_waitcnt lgkmcnt(1)
	v_pk_fma_f32 v[150:151], v[32:33], v[154:155], v[174:175]
	v_pk_fma_f32 v[186:187], v[32:33], v[158:159], v[176:177]
	v_pk_fma_f32 v[174:175], v[34:35], v[156:157], v[150:151]
	s_waitcnt lgkmcnt(0)
	v_pk_fma_f32 v[188:189], v[32:33], v[162:163], v[178:179]
	v_pk_fma_f32 v[176:177], v[34:35], v[160:161], v[186:187]
	v_pk_fma_f32 v[178:179], v[34:35], v[164:165], v[188:189]
	ds_read_b128 v[150:153], v145 offset:1216
	ds_read_b128 v[154:157], v145 offset:1472
	ds_read_b128 v[158:161], v145 offset:1728
	ds_read_b128 v[162:165], v145 offset:1984
	s_waitcnt lgkmcnt(3)
	v_pk_fma_f32 v[150:151], v[60:61], v[150:151], v[166:167]
	s_nop 0
	v_pk_fma_f32 v[166:167], v[62:63], v[152:153], v[150:151]
	s_waitcnt lgkmcnt(1)
	v_pk_fma_f32 v[150:151], v[60:61], v[154:155], v[174:175]
	v_pk_fma_f32 v[186:187], v[60:61], v[158:159], v[176:177]
	v_pk_fma_f32 v[174:175], v[62:63], v[156:157], v[150:151]
	s_waitcnt lgkmcnt(0)
	v_pk_fma_f32 v[188:189], v[60:61], v[162:163], v[178:179]
	v_pk_fma_f32 v[176:177], v[62:63], v[160:161], v[186:187]
	v_pk_fma_f32 v[178:179], v[62:63], v[164:165], v[188:189]
	ds_read_b128 v[150:153], v145 offset:1232
	ds_read_b128 v[154:157], v145 offset:1488
	ds_read_b128 v[158:161], v145 offset:1744
	ds_read_b128 v[162:165], v145 offset:2000
	s_waitcnt lgkmcnt(3)
	v_pk_fma_f32 v[150:151], v[56:57], v[150:151], v[166:167]
	s_nop 0
	v_pk_fma_f32 v[166:167], v[58:59], v[152:153], v[150:151]
	s_waitcnt lgkmcnt(1)
; DI int f2key(float f) { int b = __float_as_int(f); return b ^ ((b >> 31) & 0x7fffffff); }
; DI void phase_peer_topk(const Params& P, int layer, char* smem) {
;     ...
;           for (int g = 0; g < 4; ++g) {
;             f32x2 a0 = {0.f, 0.f}, a1 = {0.f, 0.f}, a2 = {0.f, 0.f}, a3 = {0.f, 0.f};
;             const float* k0 = kp + (c * 16 + g * 4) * 64;
; #pragma unroll
;             for (int c4 = 0; c4 < 16; ++c4) {
;               f32x4 b0 = *(const f32x4*)(k0 + c4 * 4), b1 = *(const f32x4*)(k0 + 64 + c4 * 4);
;               f32x4 b2 = *(const f32x4*)(k0 + 128 + c4 * 4), b3 = *(const f32x4*)(k0 + 192 + c4 * 4);
;               a0 += q2[2 * c4] * b0.lo; a0 += q2[2 * c4 + 1] * b0.hi;
;               a1 += q2[2 * c4] * b1.lo; a1 += q2[2 * c4 + 1] * b1.hi;
;               a2 += q2[2 * c4] * b2.lo; a2 += q2[2 * c4 + 1] * b2.hi;
;               a3 += q2[2 * c4] * b3.lo; a3 += q2[2 * c4 + 1] * b3.hi;
;             }
;             const int n = nh * 64 + qh * 32 + c * 16 + g * 4;
;             ck[g * 4 + 0] = (f2key(a0.x + a0.y) & ~127) | (127 - n);
;             ck[g * 4 + 1] = (f2key(a1.x + a1.y) & ~127) | (126 - n);
;             ck[g * 4 + 2] = (f2key(a2.x + a2.y) & ~127) | (125 - n);
;             ck[g * 4 + 3] = (f2key(a3.x + a3.y) & ~127) | (124 - n);
;           }
	v_pk_fma_f32 v[150:151], v[56:57], v[154:155], v[174:175]
	v_pk_fma_f32 v[186:187], v[56:57], v[158:159], v[176:177]
	v_pk_fma_f32 v[174:175], v[58:59], v[156:157], v[150:151]
	s_waitcnt lgkmcnt(0)
	v_pk_fma_f32 v[188:189], v[56:57], v[162:163], v[178:179]
	v_pk_fma_f32 v[176:177], v[58:59], v[160:161], v[186:187]
	v_pk_fma_f32 v[178:179], v[58:59], v[164:165], v[188:189]
	ds_read_b128 v[150:153], v145 offset:1248
	ds_read_b128 v[154:157], v145 offset:1504
	ds_read_b128 v[158:161], v145 offset:1760
	ds_read_b128 v[162:165], v145 offset:2016
	s_waitcnt lgkmcnt(3)
	v_pk_fma_f32 v[150:151], v[52:53], v[150:151], v[166:167]
	s_nop 0
	v_pk_fma_f32 v[166:167], v[54:55], v[152:153], v[150:151]
	s_waitcnt lgkmcnt(1)
	v_pk_fma_f32 v[150:151], v[52:53], v[154:155], v[174:175]
	v_pk_fma_f32 v[186:187], v[52:53], v[158:159], v[176:177]
	v_pk_fma_f32 v[174:175], v[54:55], v[156:157], v[150:151]
	s_waitcnt lgkmcnt(0)
	v_pk_fma_f32 v[188:189], v[52:53], v[162:163], v[178:179]
	v_pk_fma_f32 v[176:177], v[54:55], v[160:161], v[186:187]
	v_pk_fma_f32 v[178:179], v[54:55], v[164:165], v[188:189]
	ds_read_b128 v[150:153], v145 offset:1264
	ds_read_b128 v[154:157], v145 offset:1520
	ds_read_b128 v[158:161], v145 offset:1776
	ds_read_b128 v[162:165], v145 offset:2032
	s_waitcnt lgkmcnt(3)
	v_pk_fma_f32 v[150:151], v[48:49], v[150:151], v[166:167]
	s_nop 0
	v_pk_fma_f32 v[150:151], v[50:51], v[152:153], v[150:151]
	s_waitcnt lgkmcnt(2)
	v_pk_fma_f32 v[152:153], v[48:49], v[154:155], v[174:175]
	s_waitcnt lgkmcnt(1)
	v_pk_fma_f32 v[154:155], v[48:49], v[158:159], v[176:177]
	v_pk_fma_f32 v[152:153], v[50:51], v[156:157], v[152:153]
	v_mov_b32_e32 v159, v150
	v_mov_b32_e32 v158, v152
	v_mov_b32_e32 v150, v153
	v_pk_add_f32 v[150:151], v[158:159], v[150:151]
	v_pk_fma_f32 v[154:155], v[50:51], v[160:161], v[154:155]
	v_or_b32_e32 v160, 4, v144
	v_ashrrev_i32_e32 v152, 31, v151
	v_sub_u32_e32 v161, 0x7f, v160
	v_and_b32_e32 v152, 0x7fffff80, v152
	v_and_b32_e32 v151, 0xffffff80, v151
	s_waitcnt lgkmcnt(0)
	v_pk_fma_f32 v[156:157], v[48:49], v[162:163], v[178:179]
	v_bitop3_b32 v168, v152, v161, v151 bitop3:0xde
	v_ashrrev_i32_e32 v151, 31, v150
	v_pk_fma_f32 v[156:157], v[50:51], v[164:165], v[156:157]
	v_and_b32_e32 v151, 0x7fffff80, v151
	v_and_b32_e32 v150, 0xffffff80, v150
	v_sub_u32_e32 v152, 0x7e, v160
	v_bitop3_b32 v173, v151, v152, v150 bitop3:0xde
	v_mov_b32_e32 v150, v156
	v_mov_b32_e32 v151, v154
	v_mov_b32_e32 v154, v157
	v_pk_add_f32 v[150:151], v[150:151], v[154:155]
	v_sub_u32_e32 v152, 0x7d, v160
	v_ashrrev_i32_e32 v153, 31, v151
	v_and_b32_e32 v153, 0x7fffff80, v153
	v_and_b32_e32 v151, 0xffffff80, v151
	v_bitop3_b32 v180, v153, v152, v151 bitop3:0xde
	v_ashrrev_i32_e32 v151, 31, v150
	v_and_b32_e32 v151, 0x7fffff80, v151
	v_and_b32_e32 v150, 0xffffff80, v150
	v_sub_u32_e32 v152, 0x7c, v160
	v_bitop3_b32 v181, v151, v152, v150 bitop3:0xde
	ds_read_b128 v[150:153], v145 offset:2048
	ds_read_b128 v[154:157], v145 offset:2304
	ds_read_b128 v[158:161], v145 offset:2560
	ds_read_b128 v[162:165], v145 offset:2816
	s_waitcnt lgkmcnt(3)
	v_pk_fma_f32 v[150:151], v[12:13], v[150:151], 0 op_sel_hi:[1,1,0]
	s_nop 0
	v_pk_fma_f32 v[166:167], v[14:15], v[152:153], v[150:151]
	s_waitcnt lgkmcnt(2)
	v_pk_fma_f32 v[150:151], v[12:13], v[154:155], 0 op_sel_hi:[1,1,0]
	s_nop 0
	v_pk_fma_f32 v[174:175], v[14:15], v[156:157], v[150:151]
	s_waitcnt lgkmcnt(1)
	v_pk_fma_f32 v[150:151], v[12:13], v[158:159], 0 op_sel_hi:[1,1,0]
	s_nop 0
	v_pk_fma_f32 v[176:177], v[14:15], v[160:161], v[150:151]
	s_waitcnt lgkmcnt(0)
	v_pk_fma_f32 v[150:151], v[12:13], v[162:163], 0 op_sel_hi:[1,1,0]
	s_nop 0
	v_pk_fma_f32 v[178:179], v[14:15], v[164:165], v[150:151]
	ds_read_b128 v[150:153], v145 offset:2064
	ds_read_b128 v[154:157], v145 offset:2320
	ds_read_b128 v[158:161], v145 offset:2576
	ds_read_b128 v[162:165], v145 offset:2832
	s_waitcnt lgkmcnt(3)
	v_pk_fma_f32 v[150:151], v[8:9], v[150:151], v[166:167]
	s_nop 0
	v_pk_fma_f32 v[166:167], v[10:11], v[152:153], v[150:151]
	s_waitcnt lgkmcnt(1)
	v_pk_fma_f32 v[150:151], v[8:9], v[154:155], v[174:175]
	v_pk_fma_f32 v[186:187], v[8:9], v[158:159], v[176:177]
	v_pk_fma_f32 v[174:175], v[10:11], v[156:157], v[150:151]
	s_waitcnt lgkmcnt(0)
	v_pk_fma_f32 v[188:189], v[8:9], v[162:163], v[178:179]
	v_pk_fma_f32 v[176:177], v[10:11], v[160:161], v[186:187]
	v_pk_fma_f32 v[178:179], v[10:11], v[164:165], v[188:189]
	ds_read_b128 v[150:153], v145 offset:2080
	ds_read_b128 v[154:157], v145 offset:2336
	ds_read_b128 v[158:161], v145 offset:2592
	ds_read_b128 v[162:165], v145 offset:2848
	s_waitcnt lgkmcnt(3)
	v_pk_fma_f32 v[150:151], v[4:5], v[150:151], v[166:167]
	s_nop 0
	v_pk_fma_f32 v[166:167], v[6:7], v[152:153], v[150:151]
	s_waitcnt lgkmcnt(1)
	v_pk_fma_f32 v[150:151], v[4:5], v[154:155], v[174:175]
	v_pk_fma_f32 v[186:187], v[4:5], v[158:159], v[176:177]
	v_pk_fma_f32 v[174:175], v[6:7], v[156:157], v[150:151]
	s_waitcnt lgkmcnt(0)
	v_pk_fma_f32 v[188:189], v[4:5], v[162:163], v[178:179]
	v_pk_fma_f32 v[176:177], v[6:7], v[160:161], v[186:187]
	v_pk_fma_f32 v[178:179], v[6:7], v[164:165], v[188:189]
	ds_read_b128 v[150:153], v145 offset:2096
	ds_read_b128 v[154:157], v145 offset:2352
	ds_read_b128 v[158:161], v145 offset:2608
	ds_read_b128 v[162:165], v145 offset:2864
	s_waitcnt lgkmcnt(3)
	v_pk_fma_f32 v[150:151], v[0:1], v[150:151], v[166:167]
	s_nop 0
	v_pk_fma_f32 v[166:167], v[2:3], v[152:153], v[150:151]
	s_waitcnt lgkmcnt(1)
	v_pk_fma_f32 v[150:151], v[0:1], v[154:155], v[174:175]
	v_pk_fma_f32 v[186:187], v[0:1], v[158:159], v[176:177]
	v_pk_fma_f32 v[174:175], v[2:3], v[156:157], v[150:151]
	s_waitcnt lgkmcnt(0)
; DI int f2key(float f) { int b = __float_as_int(f); return b ^ ((b >> 31) & 0x7fffffff); }
; DI void phase_peer_topk(const Params& P, int layer, char* smem) {
;     ...
;           for (int g = 0; g < 4; ++g) {
;             f32x2 a0 = {0.f, 0.f}, a1 = {0.f, 0.f}, a2 = {0.f, 0.f}, a3 = {0.f, 0.f};
;             const float* k0 = kp + (c * 16 + g * 4) * 64;
; #pragma unroll
;             for (int c4 = 0; c4 < 16; ++c4) {
;               f32x4 b0 = *(const f32x4*)(k0 + c4 * 4), b1 = *(const f32x4*)(k0 + 64 + c4 * 4);
;               f32x4 b2 = *(const f32x4*)(k0 + 128 + c4 * 4), b3 = *(const f32x4*)(k0 + 192 + c4 * 4);
;               a0 += q2[2 * c4] * b0.lo; a0 += q2[2 * c4 + 1] * b0.hi;
;               a1 += q2[2 * c4] * b1.lo; a1 += q2[2 * c4 + 1] * b1.hi;
;               a2 += q2[2 * c4] * b2.lo; a2 += q2[2 * c4 + 1] * b2.hi;
;               a3 += q2[2 * c4] * b3.lo; a3 += q2[2 * c4 + 1] * b3.hi;
;             }
;             const int n = nh * 64 + qh * 32 + c * 16 + g * 4;
;             ck[g * 4 + 0] = (f2key(a0.x + a0.y) & ~127) | (127 - n);
;             ck[g * 4 + 1] = (f2key(a1.x + a1.y) & ~127) | (126 - n);
;             ck[g * 4 + 2] = (f2key(a2.x + a2.y) & ~127) | (125 - n);
;             ck[g * 4 + 3] = (f2key(a3.x + a3.y) & ~127) | (124 - n);
;           }
	v_pk_fma_f32 v[188:189], v[0:1], v[162:163], v[178:179]
	v_pk_fma_f32 v[176:177], v[2:3], v[160:161], v[186:187]
	v_pk_fma_f32 v[178:179], v[2:3], v[164:165], v[188:189]
	ds_read_b128 v[150:153], v145 offset:2112
	ds_read_b128 v[154:157], v145 offset:2368
	ds_read_b128 v[158:161], v145 offset:2624
	ds_read_b128 v[162:165], v145 offset:2880
	s_waitcnt lgkmcnt(3)
	v_pk_fma_f32 v[150:151], v[28:29], v[150:151], v[166:167]
	s_nop 0
	v_pk_fma_f32 v[166:167], v[30:31], v[152:153], v[150:151]
	s_waitcnt lgkmcnt(1)
	v_pk_fma_f32 v[150:151], v[28:29], v[154:155], v[174:175]
	v_pk_fma_f32 v[186:187], v[28:29], v[158:159], v[176:177]
	v_pk_fma_f32 v[174:175], v[30:31], v[156:157], v[150:151]
	s_waitcnt lgkmcnt(0)
	v_pk_fma_f32 v[188:189], v[28:29], v[162:163], v[178:179]
	v_pk_fma_f32 v[176:177], v[30:31], v[160:161], v[186:187]
	v_pk_fma_f32 v[178:179], v[30:31], v[164:165], v[188:189]
	ds_read_b128 v[150:153], v145 offset:2128
	ds_read_b128 v[154:157], v145 offset:2384
	ds_read_b128 v[158:161], v145 offset:2640
	ds_read_b128 v[162:165], v145 offset:2896
	s_waitcnt lgkmcnt(3)
	v_pk_fma_f32 v[150:151], v[24:25], v[150:151], v[166:167]
	s_nop 0
	v_pk_fma_f32 v[166:167], v[26:27], v[152:153], v[150:151]
	s_waitcnt lgkmcnt(1)
	v_pk_fma_f32 v[150:151], v[24:25], v[154:155], v[174:175]
	v_pk_fma_f32 v[186:187], v[24:25], v[158:159], v[176:177]
	v_pk_fma_f32 v[174:175], v[26:27], v[156:157], v[150:151]
	s_waitcnt lgkmcnt(0)
	v_pk_fma_f32 v[188:189], v[24:25], v[162:163], v[178:179]
	v_pk_fma_f32 v[176:177], v[26:27], v[160:161], v[186:187]
	v_pk_fma_f32 v[178:179], v[26:27], v[164:165], v[188:189]
	ds_read_b128 v[150:153], v145 offset:2144
	ds_read_b128 v[154:157], v145 offset:2400
	ds_read_b128 v[158:161], v145 offset:2656
	ds_read_b128 v[162:165], v145 offset:2912
	s_waitcnt lgkmcnt(3)
	v_pk_fma_f32 v[150:151], v[20:21], v[150:151], v[166:167]
	s_nop 0
	v_pk_fma_f32 v[166:167], v[22:23], v[152:153], v[150:151]
	s_waitcnt lgkmcnt(1)
	v_pk_fma_f32 v[150:151], v[20:21], v[154:155], v[174:175]
	v_pk_fma_f32 v[186:187], v[20:21], v[158:159], v[176:177]
	v_pk_fma_f32 v[174:175], v[22:23], v[156:157], v[150:151]
	s_waitcnt lgkmcnt(0)
	v_pk_fma_f32 v[188:189], v[20:21], v[162:163], v[178:179]
	v_pk_fma_f32 v[176:177], v[22:23], v[160:161], v[186:187]
	v_pk_fma_f32 v[178:179], v[22:23], v[164:165], v[188:189]
	ds_read_b128 v[150:153], v145 offset:2160
	ds_read_b128 v[154:157], v145 offset:2416
	ds_read_b128 v[158:161], v145 offset:2672
	ds_read_b128 v[162:165], v145 offset:2928
	s_waitcnt lgkmcnt(3)
	v_pk_fma_f32 v[150:151], v[16:17], v[150:151], v[166:167]
	s_nop 0
	v_pk_fma_f32 v[166:167], v[18:19], v[152:153], v[150:151]
	s_waitcnt lgkmcnt(1)
	v_pk_fma_f32 v[150:151], v[16:17], v[154:155], v[174:175]
	v_pk_fma_f32 v[186:187], v[16:17], v[158:159], v[176:177]
	v_pk_fma_f32 v[174:175], v[18:19], v[156:157], v[150:151]
	s_waitcnt lgkmcnt(0)
	v_pk_fma_f32 v[188:189], v[16:17], v[162:163], v[178:179]
	v_pk_fma_f32 v[176:177], v[18:19], v[160:161], v[186:187]
	v_pk_fma_f32 v[178:179], v[18:19], v[164:165], v[188:189]
	ds_read_b128 v[150:153], v145 offset:2176
	ds_read_b128 v[154:157], v145 offset:2432
	ds_read_b128 v[158:161], v145 offset:2688
	ds_read_b128 v[162:165], v145 offset:2944
	s_waitcnt lgkmcnt(3)
	v_pk_fma_f32 v[150:151], v[44:45], v[150:151], v[166:167]
	s_nop 0
	v_pk_fma_f32 v[166:167], v[46:47], v[152:153], v[150:151]
	s_waitcnt lgkmcnt(1)
	v_pk_fma_f32 v[150:151], v[44:45], v[154:155], v[174:175]
	v_pk_fma_f32 v[186:187], v[44:45], v[158:159], v[176:177]
	v_pk_fma_f32 v[174:175], v[46:47], v[156:157], v[150:151]
	s_waitcnt lgkmcnt(0)
	v_pk_fma_f32 v[188:189], v[44:45], v[162:163], v[178:179]
	v_pk_fma_f32 v[176:177], v[46:47], v[160:161], v[186:187]
	v_pk_fma_f32 v[178:179], v[46:47], v[164:165], v[188:189]
	ds_read_b128 v[150:153], v145 offset:2192
	ds_read_b128 v[154:157], v145 offset:2448
	ds_read_b128 v[158:161], v145 offset:2704
	ds_read_b128 v[162:165], v145 offset:2960
	s_waitcnt lgkmcnt(3)
	v_pk_fma_f32 v[150:151], v[40:41], v[150:151], v[166:167]
	s_nop 0
	v_pk_fma_f32 v[166:167], v[42:43], v[152:153], v[150:151]
	s_waitcnt lgkmcnt(1)
	v_pk_fma_f32 v[150:151], v[40:41], v[154:155], v[174:175]
	v_pk_fma_f32 v[186:187], v[40:41], v[158:159], v[176:177]
	v_pk_fma_f32 v[174:175], v[42:43], v[156:157], v[150:151]
	s_waitcnt lgkmcnt(0)
	v_pk_fma_f32 v[188:189], v[40:41], v[162:163], v[178:179]
	v_pk_fma_f32 v[176:177], v[42:43], v[160:161], v[186:187]
	v_pk_fma_f32 v[178:179], v[42:43], v[164:165], v[188:189]
	ds_read_b128 v[150:153], v145 offset:2208
	ds_read_b128 v[154:157], v145 offset:2464
	ds_read_b128 v[158:161], v145 offset:2720
	ds_read_b128 v[162:165], v145 offset:2976
	s_waitcnt lgkmcnt(3)
	v_pk_fma_f32 v[150:151], v[36:37], v[150:151], v[166:167]
	s_nop 0
	v_pk_fma_f32 v[166:167], v[38:39], v[152:153], v[150:151]
	s_waitcnt lgkmcnt(1)
	v_pk_fma_f32 v[150:151], v[36:37], v[154:155], v[174:175]
	v_pk_fma_f32 v[186:187], v[36:37], v[158:159], v[176:177]
	v_pk_fma_f32 v[174:175], v[38:39], v[156:157], v[150:151]
	s_waitcnt lgkmcnt(0)
	v_pk_fma_f32 v[188:189], v[36:37], v[162:163], v[178:179]
	v_pk_fma_f32 v[176:177], v[38:39], v[160:161], v[186:187]
	v_pk_fma_f32 v[178:179], v[38:39], v[164:165], v[188:189]
	ds_read_b128 v[150:153], v145 offset:2224
	ds_read_b128 v[154:157], v145 offset:2480
	ds_read_b128 v[158:161], v145 offset:2736
	ds_read_b128 v[162:165], v145 offset:2992
	s_waitcnt lgkmcnt(3)
	v_pk_fma_f32 v[150:151], v[32:33], v[150:151], v[166:167]
	s_nop 0
	v_pk_fma_f32 v[166:167], v[34:35], v[152:153], v[150:151]
	s_waitcnt lgkmcnt(1)
; DI int f2key(float f) { int b = __float_as_int(f); return b ^ ((b >> 31) & 0x7fffffff); }
; DI void phase_peer_topk(const Params& P, int layer, char* smem) {
;     ...
;           for (int g = 0; g < 4; ++g) {
;             f32x2 a0 = {0.f, 0.f}, a1 = {0.f, 0.f}, a2 = {0.f, 0.f}, a3 = {0.f, 0.f};
;             const float* k0 = kp + (c * 16 + g * 4) * 64;
; #pragma unroll
;             for (int c4 = 0; c4 < 16; ++c4) {
;               f32x4 b0 = *(const f32x4*)(k0 + c4 * 4), b1 = *(const f32x4*)(k0 + 64 + c4 * 4);
;               f32x4 b2 = *(const f32x4*)(k0 + 128 + c4 * 4), b3 = *(const f32x4*)(k0 + 192 + c4 * 4);
;               a0 += q2[2 * c4] * b0.lo; a0 += q2[2 * c4 + 1] * b0.hi;
;               a1 += q2[2 * c4] * b1.lo; a1 += q2[2 * c4 + 1] * b1.hi;
;               a2 += q2[2 * c4] * b2.lo; a2 += q2[2 * c4 + 1] * b2.hi;
;               a3 += q2[2 * c4] * b3.lo; a3 += q2[2 * c4 + 1] * b3.hi;
;             }
;             const int n = nh * 64 + qh * 32 + c * 16 + g * 4;
;             ck[g * 4 + 0] = (f2key(a0.x + a0.y) & ~127) | (127 - n);
;             ck[g * 4 + 1] = (f2key(a1.x + a1.y) & ~127) | (126 - n);
;             ck[g * 4 + 2] = (f2key(a2.x + a2.y) & ~127) | (125 - n);
;             ck[g * 4 + 3] = (f2key(a3.x + a3.y) & ~127) | (124 - n);
;           }
	v_pk_fma_f32 v[150:151], v[32:33], v[154:155], v[174:175]
	v_pk_fma_f32 v[186:187], v[32:33], v[158:159], v[176:177]
	v_pk_fma_f32 v[174:175], v[34:35], v[156:157], v[150:151]
	s_waitcnt lgkmcnt(0)
	v_pk_fma_f32 v[188:189], v[32:33], v[162:163], v[178:179]
	v_pk_fma_f32 v[176:177], v[34:35], v[160:161], v[186:187]
	v_pk_fma_f32 v[178:179], v[34:35], v[164:165], v[188:189]
	ds_read_b128 v[150:153], v145 offset:2240
	ds_read_b128 v[154:157], v145 offset:2496
	ds_read_b128 v[158:161], v145 offset:2752
	ds_read_b128 v[162:165], v145 offset:3008
	s_waitcnt lgkmcnt(3)
	v_pk_fma_f32 v[150:151], v[60:61], v[150:151], v[166:167]
	s_nop 0
	v_pk_fma_f32 v[166:167], v[62:63], v[152:153], v[150:151]
	s_waitcnt lgkmcnt(1)
	v_pk_fma_f32 v[150:151], v[60:61], v[154:155], v[174:175]
	v_pk_fma_f32 v[186:187], v[60:61], v[158:159], v[176:177]
	v_pk_fma_f32 v[174:175], v[62:63], v[156:157], v[150:151]
	s_waitcnt lgkmcnt(0)
	v_pk_fma_f32 v[188:189], v[60:61], v[162:163], v[178:179]
	v_pk_fma_f32 v[176:177], v[62:63], v[160:161], v[186:187]
	v_pk_fma_f32 v[178:179], v[62:63], v[164:165], v[188:189]
	ds_read_b128 v[150:153], v145 offset:2256
	ds_read_b128 v[154:157], v145 offset:2512
	ds_read_b128 v[158:161], v145 offset:2768
	ds_read_b128 v[162:165], v145 offset:3024
	s_waitcnt lgkmcnt(3)
	v_pk_fma_f32 v[150:151], v[56:57], v[150:151], v[166:167]
	s_nop 0
	v_pk_fma_f32 v[166:167], v[58:59], v[152:153], v[150:151]
	s_waitcnt lgkmcnt(1)
	v_pk_fma_f32 v[150:151], v[56:57], v[154:155], v[174:175]
	v_pk_fma_f32 v[186:187], v[56:57], v[158:159], v[176:177]
	v_pk_fma_f32 v[174:175], v[58:59], v[156:157], v[150:151]
	s_waitcnt lgkmcnt(0)
	v_pk_fma_f32 v[188:189], v[56:57], v[162:163], v[178:179]
	v_pk_fma_f32 v[176:177], v[58:59], v[160:161], v[186:187]
	v_pk_fma_f32 v[178:179], v[58:59], v[164:165], v[188:189]
	ds_read_b128 v[150:153], v145 offset:2272
	ds_read_b128 v[154:157], v145 offset:2528
	ds_read_b128 v[158:161], v145 offset:2784
	ds_read_b128 v[162:165], v145 offset:3040
	s_waitcnt lgkmcnt(3)
	v_pk_fma_f32 v[150:151], v[52:53], v[150:151], v[166:167]
	s_nop 0
	v_pk_fma_f32 v[166:167], v[54:55], v[152:153], v[150:151]
	s_waitcnt lgkmcnt(1)
	v_pk_fma_f32 v[150:151], v[52:53], v[154:155], v[174:175]
	v_pk_fma_f32 v[186:187], v[52:53], v[158:159], v[176:177]
	v_pk_fma_f32 v[174:175], v[54:55], v[156:157], v[150:151]
	s_waitcnt lgkmcnt(0)
	v_pk_fma_f32 v[188:189], v[52:53], v[162:163], v[178:179]
	v_pk_fma_f32 v[176:177], v[54:55], v[160:161], v[186:187]
	v_pk_fma_f32 v[178:179], v[54:55], v[164:165], v[188:189]
	ds_read_b128 v[150:153], v145 offset:2288
	ds_read_b128 v[154:157], v145 offset:2544
	ds_read_b128 v[158:161], v145 offset:2800
	ds_read_b128 v[162:165], v145 offset:3056
	s_waitcnt lgkmcnt(3)
	v_pk_fma_f32 v[150:151], v[48:49], v[150:151], v[166:167]
	s_nop 0
	v_pk_fma_f32 v[150:151], v[50:51], v[152:153], v[150:151]
	s_waitcnt lgkmcnt(2)
	v_pk_fma_f32 v[152:153], v[48:49], v[154:155], v[174:175]
	s_waitcnt lgkmcnt(1)
	v_pk_fma_f32 v[154:155], v[48:49], v[158:159], v[176:177]
	v_pk_fma_f32 v[152:153], v[50:51], v[156:157], v[152:153]
	v_mov_b32_e32 v159, v150
	v_mov_b32_e32 v158, v152
	v_mov_b32_e32 v150, v153
	v_pk_add_f32 v[150:151], v[158:159], v[150:151]
	v_pk_fma_f32 v[154:155], v[50:51], v[160:161], v[154:155]
	v_or_b32_e32 v160, 8, v144
	v_ashrrev_i32_e32 v152, 31, v151
	v_sub_u32_e32 v161, 0x7f, v160
	v_and_b32_e32 v152, 0x7fffff80, v152
	v_and_b32_e32 v151, 0xffffff80, v151
	s_waitcnt lgkmcnt(0)
	v_pk_fma_f32 v[156:157], v[48:49], v[162:163], v[178:179]
	v_bitop3_b32 v182, v152, v161, v151 bitop3:0xde
	v_ashrrev_i32_e32 v151, 31, v150
	v_pk_fma_f32 v[156:157], v[50:51], v[164:165], v[156:157]
	v_and_b32_e32 v151, 0x7fffff80, v151
	v_and_b32_e32 v150, 0xffffff80, v150
	v_sub_u32_e32 v152, 0x7e, v160
	v_bitop3_b32 v183, v151, v152, v150 bitop3:0xde
	v_mov_b32_e32 v150, v156
	v_mov_b32_e32 v151, v154
	v_mov_b32_e32 v154, v157
	v_pk_add_f32 v[150:151], v[150:151], v[154:155]
	v_sub_u32_e32 v152, 0x7d, v160
	v_ashrrev_i32_e32 v153, 31, v151
	v_and_b32_e32 v153, 0x7fffff80, v153
	v_and_b32_e32 v151, 0xffffff80, v151
	v_bitop3_b32 v184, v153, v152, v151 bitop3:0xde
	v_ashrrev_i32_e32 v151, 31, v150
	v_and_b32_e32 v151, 0x7fffff80, v151
	v_and_b32_e32 v150, 0xffffff80, v150
	v_sub_u32_e32 v152, 0x7c, v160
	v_bitop3_b32 v185, v151, v152, v150 bitop3:0xde
	ds_read_b128 v[150:153], v145 offset:3072
	ds_read_b128 v[154:157], v145 offset:3328
	ds_read_b128 v[158:161], v145 offset:3584
	ds_read_b128 v[162:165], v145 offset:3840
	s_waitcnt lgkmcnt(3)
	v_pk_fma_f32 v[150:151], v[12:13], v[150:151], 0 op_sel_hi:[1,1,0]
	s_nop 0
	v_pk_fma_f32 v[166:167], v[14:15], v[152:153], v[150:151]
	s_waitcnt lgkmcnt(2)
	v_pk_fma_f32 v[150:151], v[12:13], v[154:155], 0 op_sel_hi:[1,1,0]
	s_nop 0
	v_pk_fma_f32 v[174:175], v[14:15], v[156:157], v[150:151]
	s_waitcnt lgkmcnt(1)
	v_pk_fma_f32 v[150:151], v[12:13], v[158:159], 0 op_sel_hi:[1,1,0]
	s_nop 0
	v_pk_fma_f32 v[176:177], v[14:15], v[160:161], v[150:151]
	s_waitcnt lgkmcnt(0)
	v_pk_fma_f32 v[150:151], v[12:13], v[162:163], 0 op_sel_hi:[1,1,0]
	s_nop 0
	v_pk_fma_f32 v[178:179], v[14:15], v[164:165], v[150:151]
	ds_read_b128 v[150:153], v145 offset:3088
	ds_read_b128 v[154:157], v145 offset:3344
	ds_read_b128 v[158:161], v145 offset:3600
	ds_read_b128 v[162:165], v145 offset:3856
	s_waitcnt lgkmcnt(3)
	v_pk_fma_f32 v[150:151], v[8:9], v[150:151], v[166:167]
	s_nop 0
	v_pk_fma_f32 v[166:167], v[10:11], v[152:153], v[150:151]
	s_waitcnt lgkmcnt(1)
	v_pk_fma_f32 v[150:151], v[8:9], v[154:155], v[174:175]
	v_pk_fma_f32 v[186:187], v[8:9], v[158:159], v[176:177]
	v_pk_fma_f32 v[174:175], v[10:11], v[156:157], v[150:151]
	s_waitcnt lgkmcnt(0)
; DI int f2key(float f) { int b = __float_as_int(f); return b ^ ((b >> 31) & 0x7fffffff); }
; DI void phase_peer_topk(const Params& P, int layer, char* smem) {
;     ...
;           for (int g = 0; g < 4; ++g) {
;             f32x2 a0 = {0.f, 0.f}, a1 = {0.f, 0.f}, a2 = {0.f, 0.f}, a3 = {0.f, 0.f};
;             const float* k0 = kp + (c * 16 + g * 4) * 64;
; #pragma unroll
;             for (int c4 = 0; c4 < 16; ++c4) {
;               f32x4 b0 = *(const f32x4*)(k0 + c4 * 4), b1 = *(const f32x4*)(k0 + 64 + c4 * 4);
;               f32x4 b2 = *(const f32x4*)(k0 + 128 + c4 * 4), b3 = *(const f32x4*)(k0 + 192 + c4 * 4);
;               a0 += q2[2 * c4] * b0.lo; a0 += q2[2 * c4 + 1] * b0.hi;
;               a1 += q2[2 * c4] * b1.lo; a1 += q2[2 * c4 + 1] * b1.hi;
;               a2 += q2[2 * c4] * b2.lo; a2 += q2[2 * c4 + 1] * b2.hi;
;               a3 += q2[2 * c4] * b3.lo; a3 += q2[2 * c4 + 1] * b3.hi;
;             }
;             const int n = nh * 64 + qh * 32 + c * 16 + g * 4;
;             ck[g * 4 + 0] = (f2key(a0.x + a0.y) & ~127) | (127 - n);
;             ck[g * 4 + 1] = (f2key(a1.x + a1.y) & ~127) | (126 - n);
;             ck[g * 4 + 2] = (f2key(a2.x + a2.y) & ~127) | (125 - n);
;             ck[g * 4 + 3] = (f2key(a3.x + a3.y) & ~127) | (124 - n);
;           }
	v_pk_fma_f32 v[188:189], v[8:9], v[162:163], v[178:179]
	v_pk_fma_f32 v[176:177], v[10:11], v[160:161], v[186:187]
	v_pk_fma_f32 v[178:179], v[10:11], v[164:165], v[188:189]
	ds_read_b128 v[150:153], v145 offset:3104
	ds_read_b128 v[154:157], v145 offset:3360
	ds_read_b128 v[158:161], v145 offset:3616
	ds_read_b128 v[162:165], v145 offset:3872
	s_waitcnt lgkmcnt(3)
	v_pk_fma_f32 v[150:151], v[4:5], v[150:151], v[166:167]
	s_nop 0
	v_pk_fma_f32 v[166:167], v[6:7], v[152:153], v[150:151]
	s_waitcnt lgkmcnt(1)
	v_pk_fma_f32 v[150:151], v[4:5], v[154:155], v[174:175]
	v_pk_fma_f32 v[186:187], v[4:5], v[158:159], v[176:177]
	v_pk_fma_f32 v[174:175], v[6:7], v[156:157], v[150:151]
	s_waitcnt lgkmcnt(0)
	v_pk_fma_f32 v[188:189], v[4:5], v[162:163], v[178:179]
	v_pk_fma_f32 v[176:177], v[6:7], v[160:161], v[186:187]
	v_pk_fma_f32 v[178:179], v[6:7], v[164:165], v[188:189]
	ds_read_b128 v[150:153], v145 offset:3120
	ds_read_b128 v[154:157], v145 offset:3376
	ds_read_b128 v[158:161], v145 offset:3632
	ds_read_b128 v[162:165], v145 offset:3888
	s_waitcnt lgkmcnt(3)
	v_pk_fma_f32 v[150:151], v[0:1], v[150:151], v[166:167]
	s_nop 0
	v_pk_fma_f32 v[166:167], v[2:3], v[152:153], v[150:151]
	s_waitcnt lgkmcnt(1)
	v_pk_fma_f32 v[150:151], v[0:1], v[154:155], v[174:175]
	v_pk_fma_f32 v[186:187], v[0:1], v[158:159], v[176:177]
	v_pk_fma_f32 v[174:175], v[2:3], v[156:157], v[150:151]
	s_waitcnt lgkmcnt(0)
	v_pk_fma_f32 v[188:189], v[0:1], v[162:163], v[178:179]
	v_pk_fma_f32 v[176:177], v[2:3], v[160:161], v[186:187]
	v_pk_fma_f32 v[178:179], v[2:3], v[164:165], v[188:189]
	ds_read_b128 v[150:153], v145 offset:3136
	ds_read_b128 v[154:157], v145 offset:3392
	ds_read_b128 v[158:161], v145 offset:3648
	ds_read_b128 v[162:165], v145 offset:3904
	s_waitcnt lgkmcnt(3)
	v_pk_fma_f32 v[150:151], v[28:29], v[150:151], v[166:167]
	s_nop 0
	v_pk_fma_f32 v[166:167], v[30:31], v[152:153], v[150:151]
	s_waitcnt lgkmcnt(1)
	v_pk_fma_f32 v[150:151], v[28:29], v[154:155], v[174:175]
	v_pk_fma_f32 v[186:187], v[28:29], v[158:159], v[176:177]
	v_pk_fma_f32 v[174:175], v[30:31], v[156:157], v[150:151]
	s_waitcnt lgkmcnt(0)
	v_pk_fma_f32 v[188:189], v[28:29], v[162:163], v[178:179]
	v_pk_fma_f32 v[176:177], v[30:31], v[160:161], v[186:187]
	v_pk_fma_f32 v[178:179], v[30:31], v[164:165], v[188:189]
	ds_read_b128 v[150:153], v145 offset:3152
	ds_read_b128 v[154:157], v145 offset:3408
	ds_read_b128 v[158:161], v145 offset:3664
	ds_read_b128 v[162:165], v145 offset:3920
	s_waitcnt lgkmcnt(3)
	v_pk_fma_f32 v[150:151], v[24:25], v[150:151], v[166:167]
	s_nop 0
	v_pk_fma_f32 v[166:167], v[26:27], v[152:153], v[150:151]
	s_waitcnt lgkmcnt(1)
	v_pk_fma_f32 v[150:151], v[24:25], v[154:155], v[174:175]
	v_pk_fma_f32 v[186:187], v[24:25], v[158:159], v[176:177]
	v_pk_fma_f32 v[174:175], v[26:27], v[156:157], v[150:151]
	s_waitcnt lgkmcnt(0)
	v_pk_fma_f32 v[188:189], v[24:25], v[162:163], v[178:179]
	v_pk_fma_f32 v[176:177], v[26:27], v[160:161], v[186:187]
	v_pk_fma_f32 v[178:179], v[26:27], v[164:165], v[188:189]
	ds_read_b128 v[150:153], v145 offset:3168
	ds_read_b128 v[154:157], v145 offset:3424
	ds_read_b128 v[158:161], v145 offset:3680
	ds_read_b128 v[162:165], v145 offset:3936
	s_waitcnt lgkmcnt(3)
	v_pk_fma_f32 v[150:151], v[20:21], v[150:151], v[166:167]
	s_nop 0
	v_pk_fma_f32 v[166:167], v[22:23], v[152:153], v[150:151]
	s_waitcnt lgkmcnt(1)
	v_pk_fma_f32 v[150:151], v[20:21], v[154:155], v[174:175]
	v_pk_fma_f32 v[186:187], v[20:21], v[158:159], v[176:177]
	v_pk_fma_f32 v[174:175], v[22:23], v[156:157], v[150:151]
	s_waitcnt lgkmcnt(0)
	v_pk_fma_f32 v[188:189], v[20:21], v[162:163], v[178:179]
	v_pk_fma_f32 v[176:177], v[22:23], v[160:161], v[186:187]
	v_pk_fma_f32 v[178:179], v[22:23], v[164:165], v[188:189]
	ds_read_b128 v[150:153], v145 offset:3184
	ds_read_b128 v[154:157], v145 offset:3440
	ds_read_b128 v[158:161], v145 offset:3696
	ds_read_b128 v[162:165], v145 offset:3952
	s_waitcnt lgkmcnt(3)
	v_pk_fma_f32 v[150:151], v[16:17], v[150:151], v[166:167]
	s_nop 0
	v_pk_fma_f32 v[166:167], v[18:19], v[152:153], v[150:151]
	s_waitcnt lgkmcnt(1)
	v_pk_fma_f32 v[150:151], v[16:17], v[154:155], v[174:175]
	v_pk_fma_f32 v[186:187], v[16:17], v[158:159], v[176:177]
	v_pk_fma_f32 v[174:175], v[18:19], v[156:157], v[150:151]
	s_waitcnt lgkmcnt(0)
	v_pk_fma_f32 v[188:189], v[16:17], v[162:163], v[178:179]
	v_pk_fma_f32 v[176:177], v[18:19], v[160:161], v[186:187]
	v_pk_fma_f32 v[178:179], v[18:19], v[164:165], v[188:189]
	ds_read_b128 v[150:153], v145 offset:3200
	ds_read_b128 v[154:157], v145 offset:3456
	ds_read_b128 v[158:161], v145 offset:3712
	ds_read_b128 v[162:165], v145 offset:3968
	s_waitcnt lgkmcnt(3)
	v_pk_fma_f32 v[150:151], v[44:45], v[150:151], v[166:167]
	s_nop 0
	v_pk_fma_f32 v[166:167], v[46:47], v[152:153], v[150:151]
	s_waitcnt lgkmcnt(1)
	v_pk_fma_f32 v[150:151], v[44:45], v[154:155], v[174:175]
	v_pk_fma_f32 v[186:187], v[44:45], v[158:159], v[176:177]
	v_pk_fma_f32 v[174:175], v[46:47], v[156:157], v[150:151]
	s_waitcnt lgkmcnt(0)
	v_pk_fma_f32 v[188:189], v[44:45], v[162:163], v[178:179]
	v_pk_fma_f32 v[176:177], v[46:47], v[160:161], v[186:187]
	v_pk_fma_f32 v[178:179], v[46:47], v[164:165], v[188:189]
	ds_read_b128 v[150:153], v145 offset:3216
	ds_read_b128 v[154:157], v145 offset:3472
	ds_read_b128 v[158:161], v145 offset:3728
	ds_read_b128 v[162:165], v145 offset:3984
	s_waitcnt lgkmcnt(3)
	v_pk_fma_f32 v[150:151], v[40:41], v[150:151], v[166:167]
	s_nop 0
	v_pk_fma_f32 v[166:167], v[42:43], v[152:153], v[150:151]
	s_waitcnt lgkmcnt(1)
	v_pk_fma_f32 v[150:151], v[40:41], v[154:155], v[174:175]
	v_pk_fma_f32 v[186:187], v[40:41], v[158:159], v[176:177]
	v_pk_fma_f32 v[174:175], v[42:43], v[156:157], v[150:151]
	s_waitcnt lgkmcnt(0)
; DI int f2key(float f) { int b = __float_as_int(f); return b ^ ((b >> 31) & 0x7fffffff); }
; DI void phase_peer_topk(const Params& P, int layer, char* smem) {
;     ...
;           for (int g = 0; g < 4; ++g) {
;             f32x2 a0 = {0.f, 0.f}, a1 = {0.f, 0.f}, a2 = {0.f, 0.f}, a3 = {0.f, 0.f};
;             const float* k0 = kp + (c * 16 + g * 4) * 64;
; #pragma unroll
;             for (int c4 = 0; c4 < 16; ++c4) {
;               f32x4 b0 = *(const f32x4*)(k0 + c4 * 4), b1 = *(const f32x4*)(k0 + 64 + c4 * 4);
;               f32x4 b2 = *(const f32x4*)(k0 + 128 + c4 * 4), b3 = *(const f32x4*)(k0 + 192 + c4 * 4);
;               a0 += q2[2 * c4] * b0.lo; a0 += q2[2 * c4 + 1] * b0.hi;
;               a1 += q2[2 * c4] * b1.lo; a1 += q2[2 * c4 + 1] * b1.hi;
;               a2 += q2[2 * c4] * b2.lo; a2 += q2[2 * c4 + 1] * b2.hi;
;               a3 += q2[2 * c4] * b3.lo; a3 += q2[2 * c4 + 1] * b3.hi;
;             }
;             const int n = nh * 64 + qh * 32 + c * 16 + g * 4;
;             ck[g * 4 + 0] = (f2key(a0.x + a0.y) & ~127) | (127 - n);
;             ck[g * 4 + 1] = (f2key(a1.x + a1.y) & ~127) | (126 - n);
;             ck[g * 4 + 2] = (f2key(a2.x + a2.y) & ~127) | (125 - n);
;             ck[g * 4 + 3] = (f2key(a3.x + a3.y) & ~127) | (124 - n);
;           }
	v_pk_fma_f32 v[188:189], v[40:41], v[162:163], v[178:179]
	v_pk_fma_f32 v[176:177], v[42:43], v[160:161], v[186:187]
	v_pk_fma_f32 v[178:179], v[42:43], v[164:165], v[188:189]
	ds_read_b128 v[150:153], v145 offset:3232
	ds_read_b128 v[154:157], v145 offset:3488
	ds_read_b128 v[158:161], v145 offset:3744
	ds_read_b128 v[162:165], v145 offset:4000
	s_waitcnt lgkmcnt(3)
	v_pk_fma_f32 v[150:151], v[36:37], v[150:151], v[166:167]
	s_nop 0
	v_pk_fma_f32 v[166:167], v[38:39], v[152:153], v[150:151]
	s_waitcnt lgkmcnt(1)
	v_pk_fma_f32 v[150:151], v[36:37], v[154:155], v[174:175]
	v_pk_fma_f32 v[186:187], v[36:37], v[158:159], v[176:177]
	v_pk_fma_f32 v[174:175], v[38:39], v[156:157], v[150:151]
	s_waitcnt lgkmcnt(0)
	v_pk_fma_f32 v[188:189], v[36:37], v[162:163], v[178:179]
	v_pk_fma_f32 v[176:177], v[38:39], v[160:161], v[186:187]
	v_pk_fma_f32 v[178:179], v[38:39], v[164:165], v[188:189]
	ds_read_b128 v[150:153], v145 offset:3248
	ds_read_b128 v[154:157], v145 offset:3504
	ds_read_b128 v[158:161], v145 offset:3760
	ds_read_b128 v[162:165], v145 offset:4016
	s_waitcnt lgkmcnt(3)
	v_pk_fma_f32 v[150:151], v[32:33], v[150:151], v[166:167]
	s_nop 0
	v_pk_fma_f32 v[166:167], v[34:35], v[152:153], v[150:151]
	s_waitcnt lgkmcnt(1)
	v_pk_fma_f32 v[150:151], v[32:33], v[154:155], v[174:175]
	v_pk_fma_f32 v[186:187], v[32:33], v[158:159], v[176:177]
	v_pk_fma_f32 v[174:175], v[34:35], v[156:157], v[150:151]
	s_waitcnt lgkmcnt(0)
	v_pk_fma_f32 v[188:189], v[32:33], v[162:163], v[178:179]
	v_pk_fma_f32 v[176:177], v[34:35], v[160:161], v[186:187]
	v_pk_fma_f32 v[178:179], v[34:35], v[164:165], v[188:189]
	ds_read_b128 v[150:153], v145 offset:3264
	ds_read_b128 v[154:157], v145 offset:3520
	ds_read_b128 v[158:161], v145 offset:3776
	ds_read_b128 v[162:165], v145 offset:4032
	s_waitcnt lgkmcnt(3)
	v_pk_fma_f32 v[150:151], v[60:61], v[150:151], v[166:167]
	s_nop 0
	v_pk_fma_f32 v[166:167], v[62:63], v[152:153], v[150:151]
	s_waitcnt lgkmcnt(1)
	v_pk_fma_f32 v[150:151], v[60:61], v[154:155], v[174:175]
	v_pk_fma_f32 v[186:187], v[60:61], v[158:159], v[176:177]
	v_pk_fma_f32 v[174:175], v[62:63], v[156:157], v[150:151]
	s_waitcnt lgkmcnt(0)
	v_pk_fma_f32 v[188:189], v[60:61], v[162:163], v[178:179]
	v_pk_fma_f32 v[176:177], v[62:63], v[160:161], v[186:187]
	v_pk_fma_f32 v[178:179], v[62:63], v[164:165], v[188:189]
	ds_read_b128 v[150:153], v145 offset:3280
	ds_read_b128 v[154:157], v145 offset:3536
	ds_read_b128 v[158:161], v145 offset:3792
	ds_read_b128 v[162:165], v145 offset:4048
	s_waitcnt lgkmcnt(3)
	v_pk_fma_f32 v[150:151], v[56:57], v[150:151], v[166:167]
	s_nop 0
	v_pk_fma_f32 v[166:167], v[58:59], v[152:153], v[150:151]
	s_waitcnt lgkmcnt(1)
	v_pk_fma_f32 v[150:151], v[56:57], v[154:155], v[174:175]
	v_pk_fma_f32 v[186:187], v[56:57], v[158:159], v[176:177]
	v_pk_fma_f32 v[174:175], v[58:59], v[156:157], v[150:151]
	s_waitcnt lgkmcnt(0)
	v_pk_fma_f32 v[188:189], v[56:57], v[162:163], v[178:179]
	v_pk_fma_f32 v[176:177], v[58:59], v[160:161], v[186:187]
	v_pk_fma_f32 v[178:179], v[58:59], v[164:165], v[188:189]
	ds_read_b128 v[150:153], v145 offset:3296
	ds_read_b128 v[154:157], v145 offset:3552
	ds_read_b128 v[158:161], v145 offset:3808
	ds_read_b128 v[162:165], v145 offset:4064
	s_waitcnt lgkmcnt(3)
	v_pk_fma_f32 v[150:151], v[52:53], v[150:151], v[166:167]
	s_nop 0
	v_pk_fma_f32 v[166:167], v[54:55], v[152:153], v[150:151]
	s_waitcnt lgkmcnt(1)
	v_pk_fma_f32 v[150:151], v[52:53], v[154:155], v[174:175]
	v_pk_fma_f32 v[186:187], v[52:53], v[158:159], v[176:177]
	v_pk_fma_f32 v[174:175], v[54:55], v[156:157], v[150:151]
	s_waitcnt lgkmcnt(0)
	v_pk_fma_f32 v[188:189], v[52:53], v[162:163], v[178:179]
	v_pk_fma_f32 v[176:177], v[54:55], v[160:161], v[186:187]
	v_pk_fma_f32 v[178:179], v[54:55], v[164:165], v[188:189]
	ds_read_b128 v[150:153], v145 offset:3312
	ds_read_b128 v[154:157], v145 offset:3568
	ds_read_b128 v[158:161], v145 offset:3824
	ds_read_b128 v[162:165], v145 offset:4080
	s_waitcnt lgkmcnt(3)
	v_pk_fma_f32 v[150:151], v[48:49], v[150:151], v[166:167]
	s_nop 0
	v_pk_fma_f32 v[150:151], v[50:51], v[152:153], v[150:151]
	s_waitcnt lgkmcnt(2)
	v_pk_fma_f32 v[152:153], v[48:49], v[154:155], v[174:175]
	s_waitcnt lgkmcnt(1)
	v_pk_fma_f32 v[154:155], v[48:49], v[158:159], v[176:177]
	v_pk_fma_f32 v[152:153], v[50:51], v[156:157], v[152:153]
	v_or_b32_e32 v158, 12, v144
	v_mov_b32_e32 v144, v152
	v_mov_b32_e32 v145, v150
	v_mov_b32_e32 v150, v153
	v_pk_add_f32 v[144:145], v[144:145], v[150:151]
	v_sub_u32_e32 v159, 0x7f, v158
	v_ashrrev_i32_e32 v150, 31, v145
	v_and_b32_e32 v150, 0x7fffff80, v150
	v_and_b32_e32 v145, 0xffffff80, v145
	s_waitcnt lgkmcnt(0)
; DI int f2key(float f) { int b = __float_as_int(f); return b ^ ((b >> 31) & 0x7fffffff); }
; DI void sort16_desc(int (&a)[16]) {
; #pragma unroll
;   for (int k = 2; k <= 16; k <<= 1)
; #pragma unroll
;     for (int j = k >> 1; j > 0; j >>= 1)
; #pragma unroll
;       for (int i = 0; i < 16; ++i) {
;         int l = i ^ j;
;         if (l > i) { if ((i & k) == 0) ce_desc(a[i], a[l]); else ce_desc(a[l], a[i]); }
;       }
; }
; DI void phase_peer_topk(const Params& P, int layer, char* smem) {
;     ...
;             const int n = nh * 64 + qh * 32 + c * 16 + g * 4;
;             ck[g * 4 + 0] = (f2key(a0.x + a0.y) & ~127) | (127 - n);
;             ck[g * 4 + 1] = (f2key(a1.x + a1.y) & ~127) | (126 - n);
;             ck[g * 4 + 2] = (f2key(a2.x + a2.y) & ~127) | (125 - n);
;             ck[g * 4 + 3] = (f2key(a3.x + a3.y) & ~127) | (124 - n);
;           }
;           sort16_desc(ck);
	v_pk_fma_f32 v[156:157], v[48:49], v[162:163], v[178:179]
	v_bitop3_b32 v150, v150, v159, v145 bitop3:0xde
	v_ashrrev_i32_e32 v145, 31, v144
	v_pk_fma_f32 v[154:155], v[50:51], v[160:161], v[154:155]
	v_pk_fma_f32 v[156:157], v[50:51], v[164:165], v[156:157]
	v_and_b32_e32 v145, 0x7fffff80, v145
	v_and_b32_e32 v144, 0xffffff80, v144
	v_sub_u32_e32 v151, 0x7e, v158
	v_bitop3_b32 v151, v145, v151, v144 bitop3:0xde
	v_mov_b32_e32 v144, v156
	v_mov_b32_e32 v145, v154
	v_mov_b32_e32 v154, v157
	v_pk_add_f32 v[144:145], v[144:145], v[154:155]
	v_sub_u32_e32 v152, 0x7d, v158
	v_ashrrev_i32_e32 v153, 31, v145
	v_and_b32_e32 v153, 0x7fffff80, v153
	v_and_b32_e32 v145, 0xffffff80, v145
	v_bitop3_b32 v145, v153, v152, v145 bitop3:0xde
	v_ashrrev_i32_e32 v152, 31, v144
	v_and_b32_e32 v152, 0x7fffff80, v152
	v_and_b32_e32 v144, 0xffffff80, v144
	v_sub_u32_e32 v153, 0x7c, v158
	v_bitop3_b32 v144, v152, v153, v144 bitop3:0xde
	v_max_i32_e32 v152, v146, v147
	v_min_i32_e32 v146, v146, v147
	v_max_i32_e32 v147, v149, v148
	v_min_i32_e32 v148, v149, v148
	v_max_i32_e32 v149, v168, v173
	v_min_i32_e32 v153, v168, v173
	v_max_i32_e32 v154, v181, v180
	v_min_i32_e32 v155, v181, v180
	v_max_i32_e32 v156, v182, v183
	v_min_i32_e32 v157, v182, v183
	v_max_i32_e32 v158, v185, v184
	v_min_i32_e32 v159, v185, v184
	v_max_i32_e32 v160, v150, v151
	v_min_i32_e32 v150, v150, v151
	v_max_i32_e32 v151, v144, v145
	v_min_i32_e32 v144, v144, v145
	v_max_i32_e32 v145, v152, v148
	v_min_i32_e32 v148, v152, v148
	v_max_i32_e32 v152, v146, v147
	v_min_i32_e32 v146, v146, v147
	v_max_i32_e32 v147, v155, v149
	v_min_i32_e32 v149, v155, v149
	v_max_i32_e32 v155, v154, v153
	v_min_i32_e32 v153, v154, v153
	v_max_i32_e32 v154, v156, v159
	v_min_i32_e32 v156, v156, v159
	v_max_i32_e32 v159, v157, v158
	v_min_i32_e32 v157, v157, v158
	v_max_i32_e32 v158, v144, v160
	v_min_i32_e32 v144, v144, v160
	v_max_i32_e32 v160, v151, v150
	v_min_i32_e32 v150, v151, v150
	v_max_i32_e32 v151, v145, v152
	v_min_i32_e32 v145, v145, v152
	v_max_i32_e32 v152, v148, v146
	v_min_i32_e32 v146, v148, v146
	v_max_i32_e32 v148, v153, v149
	v_min_i32_e32 v149, v153, v149
	v_max_i32_e32 v153, v155, v147
	v_min_i32_e32 v147, v155, v147
	v_max_i32_e32 v155, v154, v159
	v_min_i32_e32 v154, v154, v159
	v_max_i32_e32 v159, v156, v157
	v_min_i32_e32 v156, v156, v157
	v_max_i32_e32 v157, v150, v144
	v_min_i32_e32 v144, v150, v144
	v_max_i32_e32 v150, v160, v158
	v_min_i32_e32 v158, v160, v158
	v_max_i32_e32 v160, v151, v149
	v_min_i32_e32 v149, v151, v149
	v_max_i32_e32 v151, v145, v148
	v_min_i32_e32 v145, v145, v148
	v_max_i32_e32 v148, v152, v147
	v_min_i32_e32 v147, v152, v147
	v_max_i32_e32 v152, v146, v153
	v_min_i32_e32 v146, v146, v153
	v_max_i32_e32 v153, v144, v155
	v_min_i32_e32 v144, v144, v155
	v_max_i32_e32 v155, v157, v154
	v_min_i32_e32 v154, v157, v154
	v_max_i32_e32 v157, v158, v159
	v_min_i32_e32 v158, v158, v159
	v_max_i32_e32 v159, v150, v156
	v_min_i32_e32 v150, v150, v156
	v_max_i32_e32 v156, v160, v148
	v_min_i32_e32 v148, v160, v148
	v_max_i32_e32 v160, v151, v152
	v_min_i32_e32 v151, v151, v152
	v_max_i32_e32 v152, v149, v147
	v_min_i32_e32 v147, v149, v147
	v_max_i32_e32 v149, v145, v146
	v_min_i32_e32 v145, v145, v146
	v_max_i32_e32 v146, v158, v144
	v_min_i32_e32 v144, v158, v144
	v_max_i32_e32 v158, v150, v154
	v_min_i32_e32 v150, v150, v154
	v_max_i32_e32 v154, v157, v153
	v_min_i32_e32 v153, v157, v153
	v_max_i32_e32 v157, v159, v155
	v_min_i32_e32 v155, v159, v155
	v_max_i32_e32 v159, v156, v160
	v_min_i32_e32 v156, v156, v160
	v_max_i32_e32 v160, v148, v151
	v_min_i32_e32 v148, v148, v151
	v_max_i32_e32 v151, v152, v149
	v_min_i32_e32 v149, v152, v149
	v_max_i32_e32 v152, v147, v145
	v_min_i32_e32 v145, v147, v145
	v_max_i32_e32 v147, v150, v144
	v_min_i32_e32 v144, v150, v144
	v_max_i32_e32 v150, v158, v146
	v_min_i32_e32 v146, v158, v146
	v_max_i32_e32 v158, v155, v153
	v_min_i32_e32 v153, v155, v153
	v_max_i32_e32 v155, v157, v154
	v_min_i32_e32 v154, v157, v154
	v_max_i32_e32 v157, v159, v144
	v_min_i32_e32 v144, v159, v144
	v_max_i32_e32 v159, v156, v147
	v_min_i32_e32 v147, v156, v147
	v_max_i32_e32 v156, v160, v146
	v_min_i32_e32 v146, v160, v146
	v_max_i32_e32 v160, v148, v150
	v_min_i32_e32 v148, v148, v150
	v_max_i32_e32 v150, v151, v153
	v_min_i32_e32 v151, v151, v153
	v_max_i32_e32 v153, v149, v158
	v_min_i32_e32 v149, v149, v158
	v_max_i32_e32 v158, v152, v154
	v_min_i32_e32 v152, v152, v154
	v_max_i32_e32 v154, v145, v155
	v_min_i32_e32 v145, v145, v155
	v_max_i32_e32 v155, v157, v150
	v_min_i32_e32 v150, v157, v150
	v_max_i32_e32 v157, v159, v153
	v_min_i32_e32 v153, v159, v153
	v_max_i32_e32 v159, v156, v158
	v_min_i32_e32 v156, v156, v158
	v_max_i32_e32 v158, v160, v154
	v_min_i32_e32 v154, v160, v154
	v_max_i32_e32 v160, v144, v151
	v_min_i32_e32 v144, v144, v151
	v_max_i32_e32 v151, v147, v149
	v_min_i32_e32 v147, v147, v149
	v_max_i32_e32 v149, v146, v152
	v_min_i32_e32 v146, v146, v152
	v_max_i32_e32 v152, v148, v145
	v_min_i32_e32 v145, v148, v145
	v_max_i32_e32 v148, v155, v159
	v_min_i32_e32 v155, v155, v159
	v_max_i32_e32 v159, v157, v158
	v_min_i32_e32 v157, v157, v158
	v_max_i32_e32 v158, v150, v156
	v_min_i32_e32 v150, v150, v156
	v_max_i32_e32 v156, v153, v154
	v_min_i32_e32 v153, v153, v154
	v_max_i32_e32 v154, v160, v149
	v_min_i32_e32 v149, v160, v149
	v_max_i32_e32 v160, v151, v152
	v_min_i32_e32 v151, v151, v152
	v_max_i32_e32 v152, v144, v146
	v_min_i32_e32 v144, v144, v146
	v_max_i32_e32 v146, v147, v145
	v_min_i32_e32 v145, v147, v145
	v_min_i32_e32 v147, v148, v159
	v_min_i32_e32 v161, v155, v157
	v_min_i32_e32 v162, v158, v156
; DI void merge16_desc(int (&run)[16], const int (&c)[16]) {
; #pragma unroll
;   for (int i = 0; i < 16; ++i) run[i] = max(run[i], c[15 - i]);
; #pragma unroll
;   for (int j = 8; j > 0; j >>= 1)
; #pragma unroll
;     for (int i = 0; i < 16; ++i) { int l = i ^ j; if (l > i) ce_desc(run[i], run[l]); }
; }
; DI void phase_peer_topk(const Params& P, int layer, char* smem) {
;     ...
;           merge16_desc(run, ck);
;         }
;       }
;       __syncthreads();
; #pragma unroll
;       for (int i = 0; i < 16; ++i) ex[(w * 16 + i) * 64 + tl] = run[i];
;       __syncthreads();
;       if (qh == 0) {
;         int oth[16];
; #pragma unroll
;         for (int i = 0; i < 16; ++i) oth[i] = ex[((w + 2) * 16 + i) * 64 + tl];
;         merge16_desc(run, oth);
; #pragma unroll
;         for (int i = 0; i < 16; ++i) ex[(w * 16 + i) * 64 + tl] = run[i];
	v_min_i32_e32 v163, v150, v153
	v_min_i32_e32 v164, v154, v160
	v_min_i32_e32 v165, v149, v151
	v_min_i32_e32 v166, v152, v146
	v_min_i32_e32 v167, v144, v145
	v_max_i32_e32 v133, v133, v167
	v_max3_i32 v136, v136, v144, v145
	v_max_i32_e32 v140, v140, v166
	v_max3_i32 v142, v142, v152, v146
	v_max_i32_e32 v141, v141, v165
	v_max3_i32 v139, v139, v149, v151
	v_max_i32_e32 v138, v138, v164
	v_max3_i32 v137, v137, v154, v160
	v_max_i32_e32 v103, v103, v163
	v_max3_i32 v106, v106, v150, v153
	v_max_i32_e32 v71, v71, v162
	v_max3_i32 v104, v104, v158, v156
	v_max_i32_e32 v67, v67, v161
	v_max3_i32 v102, v102, v155, v157
	v_max_i32_e32 v135, v135, v147
	v_max3_i32 v134, v134, v148, v159
	v_max_i32_e32 v144, v133, v103
	v_min_i32_e32 v103, v133, v103
	v_max_i32_e32 v133, v136, v106
	v_min_i32_e32 v106, v136, v106
	v_max_i32_e32 v136, v140, v71
	v_min_i32_e32 v71, v140, v71
	v_max_i32_e32 v140, v142, v104
	v_min_i32_e32 v104, v142, v104
	v_max_i32_e32 v142, v141, v67
	v_min_i32_e32 v67, v141, v67
	v_max_i32_e32 v141, v139, v102
	v_min_i32_e32 v102, v139, v102
	v_max_i32_e32 v139, v138, v135
	v_min_i32_e32 v135, v138, v135
	v_max_i32_e32 v138, v137, v134
	v_min_i32_e32 v134, v137, v134
	v_max_i32_e32 v137, v144, v142
	v_min_i32_e32 v142, v144, v142
	v_max_i32_e32 v144, v133, v141
	v_min_i32_e32 v133, v133, v141
	v_max_i32_e32 v141, v136, v139
	v_min_i32_e32 v136, v136, v139
	v_max_i32_e32 v139, v140, v138
	v_min_i32_e32 v138, v140, v138
	v_max_i32_e32 v140, v103, v67
	v_min_i32_e32 v67, v103, v67
	v_max_i32_e32 v103, v106, v102
	v_min_i32_e32 v102, v106, v102
	v_max_i32_e32 v106, v71, v135
	v_min_i32_e32 v71, v71, v135
	v_max_i32_e32 v135, v104, v134
	v_min_i32_e32 v104, v104, v134
	v_max_i32_e32 v134, v137, v141
	v_min_i32_e32 v137, v137, v141
	v_max_i32_e32 v141, v144, v139
	v_min_i32_e32 v139, v144, v139
	v_max_i32_e32 v144, v142, v136
	v_min_i32_e32 v145, v142, v136
	v_max_i32_e32 v146, v133, v138
	v_min_i32_e32 v147, v133, v138
	v_max_i32_e32 v148, v140, v106
	v_min_i32_e32 v149, v140, v106
	v_max_i32_e32 v106, v103, v135
	v_min_i32_e32 v135, v103, v135
	v_max_i32_e32 v150, v67, v71
	v_min_i32_e32 v151, v67, v71
	v_max_i32_e32 v152, v102, v104
	v_min_i32_e32 v153, v102, v104
	v_max_i32_e32 v133, v134, v141
	v_min_i32_e32 v136, v134, v141
	v_max_i32_e32 v140, v137, v139
	v_min_i32_e32 v142, v137, v139
	v_max_i32_e32 v141, v144, v146
	v_min_i32_e32 v139, v144, v146
	v_max_i32_e32 v138, v145, v147
	v_min_i32_e32 v137, v145, v147
	v_max_i32_e32 v103, v148, v106
	v_min_i32_e32 v106, v148, v106
	v_max_i32_e32 v71, v149, v135
	v_min_i32_e32 v104, v149, v135
	v_max_i32_e32 v67, v150, v152
	v_min_i32_e32 v102, v150, v152
	v_max_i32_e32 v135, v151, v153
	v_min_i32_e32 v134, v151, v153
	s_cbranch_vccz .LBB0_44
	s_mov_b32 s16, 1
	s_and_b64 vcc, exec, s[6:7]
	s_cbranch_vccz .LBB0_43
	s_barrier
	ds_write2st64_b32 v132, v133, v136 offset1:1
	ds_write2st64_b32 v132, v140, v142 offset0:2 offset1:3
	ds_write2st64_b32 v132, v141, v139 offset0:4 offset1:5
	ds_write2st64_b32 v132, v138, v137 offset0:6 offset1:7
	ds_write2st64_b32 v132, v103, v106 offset0:8 offset1:9
	ds_write2st64_b32 v132, v71, v104 offset0:10 offset1:11
	ds_write2st64_b32 v132, v67, v102 offset0:12 offset1:13
	ds_write2st64_b32 v132, v135, v134 offset0:14 offset1:15
	s_waitcnt lgkmcnt(0)
	s_barrier
	s_and_saveexec_b64 s[6:7], s[8:9]
	s_cbranch_execz .LBB0_48
	ds_read2st64_b32 v[0:1], v132 offset0:40 offset1:41
	ds_read2st64_b32 v[2:3], v132 offset0:42 offset1:43
	ds_read2st64_b32 v[4:5], v132 offset0:44 offset1:45
	ds_read2st64_b32 v[6:7], v132 offset0:46 offset1:47
	ds_read2st64_b32 v[8:9], v132 offset0:32 offset1:33
	ds_read2st64_b32 v[10:11], v132 offset0:34 offset1:35
	ds_read2st64_b32 v[12:13], v132 offset0:36 offset1:37
	ds_read2st64_b32 v[14:15], v132 offset0:38 offset1:39
	s_waitcnt lgkmcnt(4)
	v_max_i32_e32 v7, v133, v7
	v_max_i32_e32 v6, v136, v6
	v_max_i32_e32 v5, v140, v5
	v_max_i32_e32 v4, v142, v4
	v_max_i32_e32 v3, v141, v3
	v_max_i32_e32 v2, v139, v2
	v_max_i32_e32 v1, v138, v1
	v_max_i32_e32 v0, v137, v0
	s_waitcnt lgkmcnt(0)
	v_max_i32_e32 v15, v103, v15
	v_max_i32_e32 v14, v106, v14
	v_max_i32_e32 v13, v71, v13
	v_max_i32_e32 v12, v104, v12
	v_max_i32_e32 v11, v67, v11
	v_max_i32_e32 v10, v102, v10
	v_max_i32_e32 v9, v135, v9
	v_max_i32_e32 v8, v134, v8
	v_max_i32_e32 v16, v7, v15
	v_min_i32_e32 v7, v7, v15
	v_max_i32_e32 v15, v6, v14
	v_min_i32_e32 v6, v6, v14
	v_max_i32_e32 v14, v5, v13
	v_min_i32_e32 v5, v5, v13
	v_max_i32_e32 v13, v4, v12
	v_min_i32_e32 v4, v4, v12
	v_max_i32_e32 v12, v3, v11
	v_min_i32_e32 v3, v3, v11
	v_max_i32_e32 v11, v2, v10
	v_min_i32_e32 v2, v2, v10
	v_max_i32_e32 v10, v1, v9
	v_min_i32_e32 v1, v1, v9
	v_max_i32_e32 v9, v0, v8
	v_min_i32_e32 v0, v0, v8
	v_max_i32_e32 v8, v16, v12
	v_min_i32_e32 v12, v16, v12
	v_max_i32_e32 v16, v15, v11
	v_min_i32_e32 v11, v15, v11
	v_max_i32_e32 v15, v14, v10
	v_min_i32_e32 v10, v14, v10
	v_max_i32_e32 v14, v13, v9
	v_min_i32_e32 v9, v13, v9
	v_max_i32_e32 v13, v7, v3
	v_min_i32_e32 v3, v7, v3
	v_max_i32_e32 v7, v6, v2
	v_min_i32_e32 v2, v6, v2
	v_max_i32_e32 v6, v5, v1
	v_min_i32_e32 v1, v5, v1
	v_max_i32_e32 v5, v4, v0
	v_min_i32_e32 v0, v4, v0
	v_max_i32_e32 v4, v8, v15
	v_min_i32_e32 v8, v8, v15
	v_max_i32_e32 v15, v16, v14
	v_min_i32_e32 v14, v16, v14
	v_max_i32_e32 v16, v12, v10
	v_min_i32_e32 v10, v12, v10
	v_max_i32_e32 v12, v11, v9
	v_min_i32_e32 v9, v11, v9
	v_max_i32_e32 v11, v13, v6
	v_min_i32_e32 v6, v13, v6
	v_max_i32_e32 v13, v7, v5
	v_min_i32_e32 v5, v7, v5
	v_max_i32_e32 v7, v3, v1
	v_min_i32_e32 v1, v3, v1
	v_max_i32_e32 v3, v2, v0
	v_min_i32_e32 v0, v2, v0
	v_max_i32_e32 v133, v4, v15
	v_min_i32_e32 v136, v4, v15
	v_max_i32_e32 v140, v8, v14
	v_min_i32_e32 v142, v8, v14
	v_max_i32_e32 v141, v16, v12
	v_min_i32_e32 v139, v16, v12
	v_max_i32_e32 v138, v10, v9
	v_min_i32_e32 v137, v10, v9
	v_max_i32_e32 v103, v11, v13
	v_min_i32_e32 v106, v11, v13
	v_max_i32_e32 v71, v6, v5
	v_min_i32_e32 v104, v6, v5
	v_max_i32_e32 v67, v7, v3
	v_min_i32_e32 v102, v7, v3
	v_max_i32_e32 v135, v1, v0
	v_min_i32_e32 v134, v1, v0
	ds_write2st64_b32 v132, v133, v136 offset1:1
	ds_write2st64_b32 v132, v140, v142 offset0:2 offset1:3
	ds_write2st64_b32 v132, v141, v139 offset0:4 offset1:5
	ds_write2st64_b32 v132, v138, v137 offset0:6 offset1:7
	ds_write2st64_b32 v132, v103, v106 offset0:8 offset1:9
	ds_write2st64_b32 v132, v71, v104 offset0:10 offset1:11
	ds_write2st64_b32 v132, v67, v102 offset0:12 offset1:13
	ds_write2st64_b32 v132, v135, v134 offset0:14 offset1:15

; template <int BN>
; DI void gemm_main(f32x16 (&acc)[2][BN / 64], const GDesc& cur, const GDesc& nxt, GRegs<BN>& R, bool preloaded, char* smem) {
;     ...
;   for (int k0 = 0; k0 < K; k0 += 128) {
;     __syncthreads();
;     GM_STORE(R.ra0, R.rb0)
;     __syncthreads();
;     if (k0 + 128 < K) GM_LOAD(R.ra0, R.rb0, ap, wp, lda, ldw, k0 + 128)
;     else if (nxt.valid) GM_LOAD(R.ra0, R.rb0, apn, wpn, nxt.lda, nxt.ldw, 0)
;     GM_COMPUTE()
;     __syncthreads();
;     GM_STORE(R.ra1, R.rb1)
;     __syncthreads();
;     if (k0 + 192 < K) GM_LOAD(R.ra1, R.rb1, ap, wp, lda, ldw, k0 + 192)
;     else if (nxt.valid) GM_LOAD(R.ra1, R.rb1, apn, wpn, nxt.lda, nxt.ldw, 64)
;     GM_COMPUTE()
.LBB0_97:
	s_cmpk_gt_u32 s4, 0x37f
	s_cselect_b64 s[22:23], -1, 0
	s_barrier
	s_waitcnt vmcnt(7)
	ds_write_b128 v116, v[100:103]
	s_waitcnt vmcnt(9)
	ds_write_b128 v116, v[104:107] offset:4608
	s_waitcnt vmcnt(7)
	ds_write_b128 v116, v[92:95] offset:9216
	s_waitcnt vmcnt(5)
	ds_write_b128 v116, v[88:91] offset:13824
	s_waitcnt vmcnt(3)
	ds_write_b128 v116, v[96:99] offset:18432
	s_waitcnt vmcnt(1)
	ds_write_b128 v116, v[108:111] offset:23040
	s_and_b64 vcc, exec, s[22:23]
	v_lshl_add_u64 v[114:115], v[24:25], 0, v[168:169]
	v_mov_b64_e32 v[100:101], v[0:1]
	v_mov_b64_e32 v[102:103], v[8:9]
	v_mov_b64_e32 v[92:93], v[10:11]
	v_mov_b64_e32 v[90:91], v[12:13]
	v_mov_b64_e32 v[88:89], v[2:3]
	v_mov_b64_e32 v[108:109], v[14:15]
	s_cbranch_vccnz .Lmg_skip0
	s_mov_b64 s[30:31], 0x4110200
	v_lshl_add_u64 v[100:101], v[114:115], 0, s[30:31]
	s_mov_b64 s[30:31], 0x4140200
	v_lshl_add_u64 v[90:91], v[114:115], 0, s[30:31]
	s_mov_b64 s[30:31], 0x4130200
	v_lshl_add_u64 v[92:93], v[114:115], 0, s[30:31]
	s_mov_b64 s[30:31], 0x4120200
	v_lshl_add_u64 v[88:89], v[112:113], 0, v[168:169]
	v_lshl_add_u64 v[108:109], v[30:31], 0, v[168:169]
	v_lshl_add_u64 v[102:103], v[114:115], 0, s[30:31]
	s_mov_b64 s[30:31], s[34:35]
.Lmg_skip0:
	s_waitcnt lgkmcnt(0)
	s_barrier
.LBB0_99:
	s_setprio 1
	ds_read_b128 v[120:123], v117 offset:4608
	ds_read_b128 v[156:159], v117
	ds_read_b128 v[160:163], v117 offset:32
	ds_read_b128 v[164:167], v118 offset:18432
	ds_read_b128 v[174:177], v118 offset:18464
	s_waitcnt lgkmcnt(1)
	v_mfma_f32_32x32x16_bf16 v[48:63], v[156:159], v[164:167], v[48:63]
	ds_read_b128 v[156:159], v117 offset:4672
	global_load_dwordx4 v[96:99], v[88:89], off
	v_mfma_f32_32x32x16_bf16 v[32:47], v[120:123], v[164:167], v[32:47]
	ds_read_b128 v[120:123], v117 offset:4640
	global_load_dwordx4 v[104:107], v[102:103], off
	s_waitcnt lgkmcnt(2)
	v_mfma_f32_32x32x16_bf16 v[48:63], v[160:163], v[174:177], v[48:63]
	ds_read_b128 v[160:163], v118 offset:18496
	global_load_dwordx4 v[88:91], v[90:91], off
	s_waitcnt lgkmcnt(1)
	v_mfma_f32_32x32x16_bf16 v[32:47], v[120:123], v[174:177], v[32:47]
	ds_read_b128 v[120:123], v117 offset:64
	global_load_dwordx4 v[92:95], v[92:93], off
	s_waitcnt lgkmcnt(0)
	v_mfma_f32_32x32x16_bf16 v[48:63], v[120:123], v[160:163], v[48:63]
	global_load_dwordx4 v[100:103], v[100:101], off
	v_mfma_f32_32x32x16_bf16 v[32:47], v[156:159], v[160:163], v[32:47]
	ds_read_b128 v[160:163], v118 offset:18528
	ds_read_b128 v[156:159], v117 offset:4704
	global_load_dwordx4 v[108:111], v[108:109], off
	s_waitcnt lgkmcnt(0)
	v_mfma_f32_32x32x16_bf16 v[32:47], v[156:159], v[160:163], v[32:47]
	ds_read_b128 v[120:123], v117 offset:96
	s_waitcnt lgkmcnt(0)
	v_mfma_f32_32x32x16_bf16 v[48:63], v[120:123], v[160:163], v[48:63]
	s_setprio 0
	s_barrier
	ds_write_b128 v116, v[76:79]
	ds_write_b128 v116, v[68:71] offset:9216
	ds_write_b128 v116, v[64:67] offset:13824
	s_waitcnt vmcnt(6)
	ds_write_b128 v116, v[84:87] offset:23040
	s_cmpk_gt_u32 s4, 0x33f
	v_mov_b64_e32 v[76:77], v[4:5]
	v_mov_b64_e32 v[78:79], v[16:17]
	v_mov_b64_e32 v[68:69], v[18:19]
	v_mov_b64_e32 v[66:67], v[20:21]
	v_mov_b64_e32 v[64:65], v[6:7]
	v_mov_b64_e32 v[84:85], v[22:23]
	ds_write_b128 v116, v[80:83] offset:4608
	ds_write_b128 v116, v[72:75] offset:18432
	s_cbranch_scc1 .Lmg_skip1
	s_mov_b64 s[30:31], 0x4110280
	v_lshl_add_u64 v[76:77], v[114:115], 0, s[30:31]
	s_mov_b64 s[30:31], 0x4140280
	v_lshl_add_u64 v[66:67], v[114:115], 0, s[30:31]
	s_mov_b64 s[30:31], 0x4130280
	v_lshl_add_u64 v[68:69], v[114:115], 0, s[30:31]
	s_mov_b64 s[30:31], 0x4120280
	v_lshl_add_u64 v[64:65], v[28:29], 0, v[168:169]
	v_lshl_add_u64 v[84:85], v[26:27], 0, v[168:169]
	v_lshl_add_u64 v[78:79], v[114:115], 0, s[30:31]
	s_mov_b64 s[30:31], s[34:35]
.Lmg_skip1:
	s_waitcnt lgkmcnt(0)
	s_barrier
	s_branch .LBB0_96
